# LoRA decay epilogue: w0 loaded once up front instead of reloaded behind 16 stores with vmcnt(0) per 32-row block
# baseline (speedup 1.0000x reference)
.LBB0_499:
	s_andn2_b64 vcc, exec, s[2:3]
	s_cbranch_vccnz .LBB0_501
	v_lshl_add_u64 v[104:105], v[100:101], 2, s[58:59]
	global_load_dword v236, v[104:105], off
	global_load_dword v237, v[104:105], off offset:128
	s_nop 0
	s_waitcnt vmcnt(0)
	v_mov_b32_e32 v101, v236
	v_add_f32_e32 v103, v82, v101
	s_mov_b32 s0, 0xbfb8aa3b
	v_max_f32_e64 v106, -v103, 0
	v_mul_f32_e64 v103, |v103|, s0
	v_exp_f32_e32 v103, v103
	s_mov_b32 s1, 0x3f317217
	v_add_f32_e32 v103, 1.0, v103
	v_cmp_gt_f32_e32 vcc, s31, v103
	s_nop 1
	v_cndmask_b32_e64 v107, 0, 32, vcc
	v_ldexp_f32 v103, v103, v107
	v_log_f32_e32 v103, v103
	s_nop 0
	v_mul_f32_e32 v107, 0x3f317217, v103
	v_fma_f32 v107, v103, s1, -v107
	v_fmac_f32_e32 v107, 0x3377d1cf, v103
	v_fmac_f32_e32 v107, 0x3f317217, v103
	v_cmp_lt_f32_e64 s[42:43], |v103|, s33
	s_nop 1
	v_cndmask_b32_e64 v103, v103, v107, s[42:43]
	v_cndmask_b32_e32 v107, 0, v199, vcc
	v_sub_f32_e32 v103, v103, v107
	v_add_f32_e32 v103, v106, v103
	v_sub_f32_e32 v103, -0.5, v103
	v_mul_f32_e32 v103, 0x3fb8aa3b, v103
	v_exp_f32_e32 v103, v103
	s_nop 0
	v_mul_f32_e32 v103, 0xbfb8aa3b, v103
	v_exp_f32_e32 v106, v103
	v_mov_b32_e32 v103, v1
	v_lshl_add_u64 v[102:103], v[102:103], 2, s[48:49]
	global_store_dword v[102:103], v106, off
	v_add_f32_e32 v102, v83, v101
	v_max_f32_e64 v103, -v102, 0
	v_mul_f32_e64 v102, |v102|, s0
	v_exp_f32_e32 v102, v102
	s_nop 0
	v_add_f32_e32 v102, 1.0, v102
	v_cmp_gt_f32_e32 vcc, s31, v102
	s_nop 1
	v_cndmask_b32_e64 v106, 0, 32, vcc
	v_ldexp_f32 v102, v102, v106
	v_log_f32_e32 v102, v102
	s_nop 0
	v_mul_f32_e32 v106, 0x3f317217, v102
	v_fma_f32 v106, v102, s1, -v106
	v_fmac_f32_e32 v106, 0x3377d1cf, v102
	v_fmac_f32_e32 v106, 0x3f317217, v102
	v_cmp_lt_f32_e64 s[42:43], |v102|, s33
	s_nop 1
	v_cndmask_b32_e64 v102, v102, v106, s[42:43]
	v_cndmask_b32_e32 v106, 0, v199, vcc
	v_sub_f32_e32 v102, v102, v106
	v_add_f32_e32 v102, v103, v102
	v_sub_f32_e32 v102, -0.5, v102
	v_mul_f32_e32 v102, 0x3fb8aa3b, v102
	v_exp_f32_e32 v102, v102
	v_mov_b32_e32 v103, v1
	v_mul_f32_e32 v102, 0xbfb8aa3b, v102
	v_exp_f32_e32 v106, v102
	v_add_u32_e32 v102, v100, v159
	v_lshl_add_u64 v[102:103], v[102:103], 2, s[48:49]
	global_store_dword v[102:103], v106, off
	v_add_f32_e32 v102, v84, v101
	v_max_f32_e64 v103, -v102, 0
	v_mul_f32_e64 v102, |v102|, s0
	v_exp_f32_e32 v102, v102
	s_nop 0
	v_add_f32_e32 v102, 1.0, v102
	v_cmp_gt_f32_e32 vcc, s31, v102
	s_nop 1
	v_cndmask_b32_e64 v106, 0, 32, vcc
	v_ldexp_f32 v102, v102, v106
	v_log_f32_e32 v102, v102
	s_nop 0
	v_mul_f32_e32 v106, 0x3f317217, v102
	v_fma_f32 v106, v102, s1, -v106
	v_fmac_f32_e32 v106, 0x3377d1cf, v102
	v_fmac_f32_e32 v106, 0x3f317217, v102
	v_cmp_lt_f32_e64 s[42:43], |v102|, s33
	s_nop 1
	v_cndmask_b32_e64 v102, v102, v106, s[42:43]
	v_cndmask_b32_e32 v106, 0, v199, vcc
	v_sub_f32_e32 v102, v102, v106
	v_add_f32_e32 v102, v103, v102
	v_sub_f32_e32 v102, -0.5, v102
	v_mul_f32_e32 v102, 0x3fb8aa3b, v102
	v_exp_f32_e32 v102, v102
	v_mov_b32_e32 v103, v1
	v_mul_f32_e32 v102, 0xbfb8aa3b, v102
	v_exp_f32_e32 v106, v102
	v_add_u32_e32 v102, v100, v158
	v_lshl_add_u64 v[102:103], v[102:103], 2, s[48:49]
	global_store_dword v[102:103], v106, off
	v_add_f32_e32 v102, v85, v101
	v_max_f32_e64 v103, -v102, 0
	v_mul_f32_e64 v102, |v102|, s0
	v_exp_f32_e32 v102, v102
	s_nop 0
	v_add_f32_e32 v102, 1.0, v102
	v_cmp_gt_f32_e32 vcc, s31, v102
	s_nop 1
	v_cndmask_b32_e64 v106, 0, 32, vcc
	v_ldexp_f32 v102, v102, v106
	v_log_f32_e32 v102, v102
	s_nop 0
	v_mul_f32_e32 v106, 0x3f317217, v102
	v_fma_f32 v106, v102, s1, -v106
	v_fmac_f32_e32 v106, 0x3377d1cf, v102
	v_fmac_f32_e32 v106, 0x3f317217, v102
	v_cmp_lt_f32_e64 s[42:43], |v102|, s33
	s_nop 1
	v_cndmask_b32_e64 v102, v102, v106, s[42:43]
	v_cndmask_b32_e32 v106, 0, v199, vcc
	v_sub_f32_e32 v102, v102, v106
	v_add_f32_e32 v102, v103, v102
	v_sub_f32_e32 v102, -0.5, v102
	v_mul_f32_e32 v102, 0x3fb8aa3b, v102
	v_exp_f32_e32 v102, v102
	v_mov_b32_e32 v103, v1
	v_mul_f32_e32 v102, 0xbfb8aa3b, v102
	v_exp_f32_e32 v106, v102
	v_add_u32_e32 v102, v100, v157
	v_lshl_add_u64 v[102:103], v[102:103], 2, s[48:49]
	global_store_dword v[102:103], v106, off
	v_add_f32_e32 v102, v86, v101
	v_max_f32_e64 v103, -v102, 0
	v_mul_f32_e64 v102, |v102|, s0
	v_exp_f32_e32 v102, v102
	s_nop 0
	v_add_f32_e32 v102, 1.0, v102
	v_cmp_gt_f32_e32 vcc, s31, v102
	s_nop 1
	v_cndmask_b32_e64 v106, 0, 32, vcc
	v_ldexp_f32 v102, v102, v106
	v_log_f32_e32 v102, v102
	s_nop 0
	v_mul_f32_e32 v106, 0x3f317217, v102
	v_fma_f32 v106, v102, s1, -v106
	v_fmac_f32_e32 v106, 0x3377d1cf, v102
	v_fmac_f32_e32 v106, 0x3f317217, v102
	v_cmp_lt_f32_e64 s[42:43], |v102|, s33
	s_nop 1
	v_cndmask_b32_e64 v102, v102, v106, s[42:43]
	v_cndmask_b32_e32 v106, 0, v199, vcc
	v_sub_f32_e32 v102, v102, v106
	v_add_f32_e32 v102, v103, v102
	v_sub_f32_e32 v102, -0.5, v102
	v_mul_f32_e32 v102, 0x3fb8aa3b, v102
	v_exp_f32_e32 v102, v102
	v_mov_b32_e32 v103, v1
	v_mul_f32_e32 v102, 0xbfb8aa3b, v102
	v_exp_f32_e32 v106, v102
	v_add_u32_e32 v102, v100, v156
	v_lshl_add_u64 v[102:103], v[102:103], 2, s[48:49]
	global_store_dword v[102:103], v106, off
	v_add_f32_e32 v102, v87, v101
	v_max_f32_e64 v103, -v102, 0
	v_mul_f32_e64 v102, |v102|, s0
	v_exp_f32_e32 v102, v102
	s_nop 0
	v_add_f32_e32 v102, 1.0, v102
	v_cmp_gt_f32_e32 vcc, s31, v102
	s_nop 1
	v_cndmask_b32_e64 v106, 0, 32, vcc
	v_ldexp_f32 v102, v102, v106
	v_log_f32_e32 v102, v102
	s_nop 0
	v_mul_f32_e32 v106, 0x3f317217, v102
	v_fma_f32 v106, v102, s1, -v106
	v_fmac_f32_e32 v106, 0x3377d1cf, v102
	v_fmac_f32_e32 v106, 0x3f317217, v102
	v_cmp_lt_f32_e64 s[42:43], |v102|, s33
	s_nop 1
	v_cndmask_b32_e64 v102, v102, v106, s[42:43]
	v_cndmask_b32_e32 v106, 0, v199, vcc
	v_sub_f32_e32 v102, v102, v106
	v_add_f32_e32 v102, v103, v102
	v_sub_f32_e32 v102, -0.5, v102
	v_mul_f32_e32 v102, 0x3fb8aa3b, v102
	v_exp_f32_e32 v102, v102
	v_mov_b32_e32 v103, v1
	v_mul_f32_e32 v102, 0xbfb8aa3b, v102
	v_exp_f32_e32 v106, v102
	v_add_u32_e32 v102, v100, v155
	v_lshl_add_u64 v[102:103], v[102:103], 2, s[48:49]
	global_store_dword v[102:103], v106, off
	v_add_f32_e32 v102, v88, v101
	v_max_f32_e64 v103, -v102, 0
	v_mul_f32_e64 v102, |v102|, s0
	v_exp_f32_e32 v102, v102
	s_nop 0
	v_add_f32_e32 v102, 1.0, v102
	v_cmp_gt_f32_e32 vcc, s31, v102
	s_nop 1
	v_cndmask_b32_e64 v106, 0, 32, vcc
	v_ldexp_f32 v102, v102, v106
	v_log_f32_e32 v102, v102
	s_nop 0
	v_mul_f32_e32 v106, 0x3f317217, v102
	v_fma_f32 v106, v102, s1, -v106
	v_fmac_f32_e32 v106, 0x3377d1cf, v102
	v_fmac_f32_e32 v106, 0x3f317217, v102
	v_cmp_lt_f32_e64 s[42:43], |v102|, s33
	s_nop 1
	v_cndmask_b32_e64 v102, v102, v106, s[42:43]
	v_cndmask_b32_e32 v106, 0, v199, vcc
	v_sub_f32_e32 v102, v102, v106
	v_add_f32_e32 v102, v103, v102
	v_sub_f32_e32 v102, -0.5, v102
	v_mul_f32_e32 v102, 0x3fb8aa3b, v102
	v_exp_f32_e32 v102, v102
	v_mov_b32_e32 v103, v1
	v_mul_f32_e32 v102, 0xbfb8aa3b, v102
	v_exp_f32_e32 v106, v102
	v_add_u32_e32 v102, v100, v154
	v_lshl_add_u64 v[102:103], v[102:103], 2, s[48:49]
	global_store_dword v[102:103], v106, off
	v_add_f32_e32 v102, v89, v101
	v_max_f32_e64 v103, -v102, 0
	v_mul_f32_e64 v102, |v102|, s0
	v_exp_f32_e32 v102, v102
	s_nop 0
	v_add_f32_e32 v102, 1.0, v102
	v_cmp_gt_f32_e32 vcc, s31, v102
	s_nop 1
	v_cndmask_b32_e64 v106, 0, 32, vcc
	v_ldexp_f32 v102, v102, v106
	v_log_f32_e32 v102, v102
	s_nop 0
	v_mul_f32_e32 v106, 0x3f317217, v102
	v_fma_f32 v106, v102, s1, -v106
	v_fmac_f32_e32 v106, 0x3377d1cf, v102
	v_fmac_f32_e32 v106, 0x3f317217, v102
	v_cmp_lt_f32_e64 s[42:43], |v102|, s33
	s_nop 1
	v_cndmask_b32_e64 v102, v102, v106, s[42:43]
	v_cndmask_b32_e32 v106, 0, v199, vcc
	v_sub_f32_e32 v102, v102, v106
	v_add_f32_e32 v102, v103, v102
	v_sub_f32_e32 v102, -0.5, v102
	v_mul_f32_e32 v102, 0x3fb8aa3b, v102
	v_exp_f32_e32 v102, v102
	v_mov_b32_e32 v103, v1
	v_mul_f32_e32 v102, 0xbfb8aa3b, v102
	v_exp_f32_e32 v106, v102
	v_add_u32_e32 v102, v100, v153
	v_lshl_add_u64 v[102:103], v[102:103], 2, s[48:49]
	global_store_dword v[102:103], v106, off
	v_add_f32_e32 v102, v90, v101
	v_max_f32_e64 v103, -v102, 0
	v_mul_f32_e64 v102, |v102|, s0
	v_exp_f32_e32 v102, v102
	s_nop 0
	v_add_f32_e32 v102, 1.0, v102
	v_cmp_gt_f32_e32 vcc, s31, v102
	s_nop 1
	v_cndmask_b32_e64 v106, 0, 32, vcc
	v_ldexp_f32 v102, v102, v106
	v_log_f32_e32 v102, v102
	s_nop 0
	v_mul_f32_e32 v106, 0x3f317217, v102
	v_fma_f32 v106, v102, s1, -v106
	v_fmac_f32_e32 v106, 0x3377d1cf, v102
	v_fmac_f32_e32 v106, 0x3f317217, v102
	v_cmp_lt_f32_e64 s[42:43], |v102|, s33
	s_nop 1
	v_cndmask_b32_e64 v102, v102, v106, s[42:43]
	v_cndmask_b32_e32 v106, 0, v199, vcc
	v_sub_f32_e32 v102, v102, v106
	v_add_f32_e32 v102, v103, v102
	v_sub_f32_e32 v102, -0.5, v102
	v_mul_f32_e32 v102, 0x3fb8aa3b, v102
	v_exp_f32_e32 v102, v102
	v_mov_b32_e32 v103, v1
	v_mul_f32_e32 v102, 0xbfb8aa3b, v102
	v_exp_f32_e32 v106, v102
	v_add_u32_e32 v102, v100, v152
	v_lshl_add_u64 v[102:103], v[102:103], 2, s[48:49]
	global_store_dword v[102:103], v106, off
	v_add_f32_e32 v102, v91, v101
	v_max_f32_e64 v103, -v102, 0
	v_mul_f32_e64 v102, |v102|, s0
	v_exp_f32_e32 v102, v102
	s_nop 0
	v_add_f32_e32 v102, 1.0, v102
	v_cmp_gt_f32_e32 vcc, s31, v102
	s_nop 1
	v_cndmask_b32_e64 v106, 0, 32, vcc
	v_ldexp_f32 v102, v102, v106
	v_log_f32_e32 v102, v102
	s_nop 0
	v_mul_f32_e32 v106, 0x3f317217, v102
	v_fma_f32 v106, v102, s1, -v106
	v_fmac_f32_e32 v106, 0x3377d1cf, v102
	v_fmac_f32_e32 v106, 0x3f317217, v102
	v_cmp_lt_f32_e64 s[42:43], |v102|, s33
	s_nop 1
	v_cndmask_b32_e64 v102, v102, v106, s[42:43]
	v_cndmask_b32_e32 v106, 0, v199, vcc
	v_sub_f32_e32 v102, v102, v106
	v_add_f32_e32 v102, v103, v102
	v_sub_f32_e32 v102, -0.5, v102
	v_mul_f32_e32 v102, 0x3fb8aa3b, v102
	v_exp_f32_e32 v102, v102
	v_mov_b32_e32 v103, v1
	v_mul_f32_e32 v102, 0xbfb8aa3b, v102
	v_exp_f32_e32 v106, v102
	v_add_u32_e32 v102, v100, v151
	v_lshl_add_u64 v[102:103], v[102:103], 2, s[48:49]
	global_store_dword v[102:103], v106, off
	v_add_f32_e32 v102, v92, v101
	v_max_f32_e64 v103, -v102, 0
	v_mul_f32_e64 v102, |v102|, s0
	v_exp_f32_e32 v102, v102
	s_nop 0
	v_add_f32_e32 v102, 1.0, v102
	v_cmp_gt_f32_e32 vcc, s31, v102
	s_nop 1
	v_cndmask_b32_e64 v106, 0, 32, vcc
	v_ldexp_f32 v102, v102, v106
	v_log_f32_e32 v102, v102
	s_nop 0
	v_mul_f32_e32 v106, 0x3f317217, v102
	v_fma_f32 v106, v102, s1, -v106
	v_fmac_f32_e32 v106, 0x3377d1cf, v102
	v_fmac_f32_e32 v106, 0x3f317217, v102
	v_cmp_lt_f32_e64 s[42:43], |v102|, s33
	s_nop 1
	v_cndmask_b32_e64 v102, v102, v106, s[42:43]
	v_cndmask_b32_e32 v106, 0, v199, vcc
	v_sub_f32_e32 v102, v102, v106
	v_add_f32_e32 v102, v103, v102
	v_sub_f32_e32 v102, -0.5, v102
	v_mul_f32_e32 v102, 0x3fb8aa3b, v102
	v_exp_f32_e32 v102, v102
	v_mov_b32_e32 v103, v1
	v_mul_f32_e32 v102, 0xbfb8aa3b, v102
	v_exp_f32_e32 v106, v102
	v_add_u32_e32 v102, v100, v150
	v_lshl_add_u64 v[102:103], v[102:103], 2, s[48:49]
	global_store_dword v[102:103], v106, off
	v_add_f32_e32 v102, v93, v101
	v_max_f32_e64 v103, -v102, 0
	v_mul_f32_e64 v102, |v102|, s0
	v_exp_f32_e32 v102, v102
	s_nop 0
	v_add_f32_e32 v102, 1.0, v102
	v_cmp_gt_f32_e32 vcc, s31, v102
	s_nop 1
	v_cndmask_b32_e64 v106, 0, 32, vcc
	v_ldexp_f32 v102, v102, v106
	v_log_f32_e32 v102, v102
	s_nop 0
	v_mul_f32_e32 v106, 0x3f317217, v102
	v_fma_f32 v106, v102, s1, -v106
	v_fmac_f32_e32 v106, 0x3377d1cf, v102
	v_fmac_f32_e32 v106, 0x3f317217, v102
	v_cmp_lt_f32_e64 s[42:43], |v102|, s33
	s_nop 1
	v_cndmask_b32_e64 v102, v102, v106, s[42:43]
	v_cndmask_b32_e32 v106, 0, v199, vcc
	v_sub_f32_e32 v102, v102, v106
	v_add_f32_e32 v102, v103, v102
	v_sub_f32_e32 v102, -0.5, v102
	v_mul_f32_e32 v102, 0x3fb8aa3b, v102
	v_exp_f32_e32 v102, v102
	v_mov_b32_e32 v103, v1
	v_mul_f32_e32 v102, 0xbfb8aa3b, v102
	v_exp_f32_e32 v106, v102
	v_add_u32_e32 v102, v100, v149
	v_lshl_add_u64 v[102:103], v[102:103], 2, s[48:49]
	global_store_dword v[102:103], v106, off
	v_add_f32_e32 v102, v94, v101
	v_max_f32_e64 v103, -v102, 0
	v_mul_f32_e64 v102, |v102|, s0
	v_exp_f32_e32 v102, v102
	s_nop 0
	v_add_f32_e32 v102, 1.0, v102
	v_cmp_gt_f32_e32 vcc, s31, v102
	s_nop 1
	v_cndmask_b32_e64 v106, 0, 32, vcc
	v_ldexp_f32 v102, v102, v106
	v_log_f32_e32 v102, v102
	s_nop 0
	v_mul_f32_e32 v106, 0x3f317217, v102
	v_fma_f32 v106, v102, s1, -v106
	v_fmac_f32_e32 v106, 0x3377d1cf, v102
	v_fmac_f32_e32 v106, 0x3f317217, v102
	v_cmp_lt_f32_e64 s[42:43], |v102|, s33
	s_nop 1
	v_cndmask_b32_e64 v102, v102, v106, s[42:43]
	v_cndmask_b32_e32 v106, 0, v199, vcc
	v_sub_f32_e32 v102, v102, v106
	v_add_f32_e32 v102, v103, v102
	v_sub_f32_e32 v102, -0.5, v102
	v_mul_f32_e32 v102, 0x3fb8aa3b, v102
	v_exp_f32_e32 v102, v102
	v_mov_b32_e32 v103, v1
	v_mul_f32_e32 v102, 0xbfb8aa3b, v102
	v_exp_f32_e32 v106, v102
	v_add_u32_e32 v102, v100, v148
	v_lshl_add_u64 v[102:103], v[102:103], 2, s[48:49]
	global_store_dword v[102:103], v106, off
	v_add_f32_e32 v102, v95, v101
	v_max_f32_e64 v103, -v102, 0
	v_mul_f32_e64 v102, |v102|, s0
	v_exp_f32_e32 v102, v102
	s_nop 0
	v_add_f32_e32 v102, 1.0, v102
	v_cmp_gt_f32_e32 vcc, s31, v102
	s_nop 1
	v_cndmask_b32_e64 v106, 0, 32, vcc
	v_ldexp_f32 v102, v102, v106
	v_log_f32_e32 v102, v102
	s_nop 0
	v_mul_f32_e32 v106, 0x3f317217, v102
	v_fma_f32 v106, v102, s1, -v106
	v_fmac_f32_e32 v106, 0x3377d1cf, v102
	v_fmac_f32_e32 v106, 0x3f317217, v102
	v_cmp_lt_f32_e64 s[42:43], |v102|, s33
	s_nop 1
	v_cndmask_b32_e64 v102, v102, v106, s[42:43]
	v_cndmask_b32_e32 v106, 0, v199, vcc
	v_sub_f32_e32 v102, v102, v106
	v_add_f32_e32 v102, v103, v102
	v_sub_f32_e32 v102, -0.5, v102
	v_mul_f32_e32 v102, 0x3fb8aa3b, v102
	v_exp_f32_e32 v102, v102
	v_mov_b32_e32 v103, v1
	v_mul_f32_e32 v102, 0xbfb8aa3b, v102
	v_exp_f32_e32 v106, v102
	v_add_u32_e32 v102, v100, v113
	v_lshl_add_u64 v[102:103], v[102:103], 2, s[48:49]
	global_store_dword v[102:103], v106, off
	v_add_f32_e32 v102, v96, v101
	v_max_f32_e64 v103, -v102, 0
	v_mul_f32_e64 v102, |v102|, s0
	v_exp_f32_e32 v102, v102
	v_add_f32_e32 v101, v97, v101
	v_add_f32_e32 v102, 1.0, v102
	v_cmp_gt_f32_e32 vcc, s31, v102
	s_nop 1
	v_cndmask_b32_e64 v106, 0, 32, vcc
	v_ldexp_f32 v102, v102, v106
	v_log_f32_e32 v102, v102
	s_nop 0
	v_mul_f32_e32 v106, 0x3f317217, v102
	v_fma_f32 v106, v102, s1, -v106
	v_fmac_f32_e32 v106, 0x3377d1cf, v102
	v_fmac_f32_e32 v106, 0x3f317217, v102
	v_cmp_lt_f32_e64 s[42:43], |v102|, s33
	s_nop 1
	v_cndmask_b32_e64 v102, v102, v106, s[42:43]
	v_cndmask_b32_e32 v106, 0, v199, vcc
	v_sub_f32_e32 v102, v102, v106
	v_add_f32_e32 v102, v103, v102
	v_sub_f32_e32 v102, -0.5, v102
	v_mul_f32_e32 v102, 0x3fb8aa3b, v102
	v_exp_f32_e32 v102, v102
	v_mov_b32_e32 v103, v1
	v_mul_f32_e32 v102, 0xbfb8aa3b, v102
	v_exp_f32_e32 v106, v102
	v_add_u32_e32 v102, v100, v112
	v_lshl_add_u64 v[102:103], v[102:103], 2, s[48:49]
	global_store_dword v[102:103], v106, off
	v_max_f32_e64 v102, -v101, 0
	v_mul_f32_e64 v101, |v101|, s0
	v_exp_f32_e32 v101, v101
	s_nop 0
	v_add_f32_e32 v101, 1.0, v101
	v_cmp_gt_f32_e32 vcc, s31, v101
	s_nop 1
	v_cndmask_b32_e64 v103, 0, 32, vcc
	v_ldexp_f32 v101, v101, v103
	v_log_f32_e32 v101, v101
	s_nop 0
	v_mul_f32_e32 v103, 0x3f317217, v101
	v_fma_f32 v103, v101, s1, -v103
	v_fmac_f32_e32 v103, 0x3377d1cf, v101
	v_fmac_f32_e32 v103, 0x3f317217, v101
	v_cmp_lt_f32_e64 s[42:43], |v101|, s33
	s_nop 1
	v_cndmask_b32_e64 v101, v101, v103, s[42:43]
	v_cndmask_b32_e32 v103, 0, v199, vcc
	v_sub_f32_e32 v101, v101, v103
	v_add_f32_e32 v101, v102, v101
	v_sub_f32_e32 v101, -0.5, v101
	v_mul_f32_e32 v101, 0x3fb8aa3b, v101
	v_exp_f32_e32 v101, v101
	v_add_u32_e32 v102, v100, v111
	v_mov_b32_e32 v103, v1
	v_lshl_add_u64 v[102:103], v[102:103], 2, s[48:49]
	v_mul_f32_e32 v101, 0xbfb8aa3b, v101
	v_exp_f32_e32 v101, v101
	global_store_dword v[102:103], v101, off
	v_or_b32_e32 v101, 32, v100
	v_mov_b32_e32 v102, v237
	v_add_f32_e32 v103, v66, v102
	v_max_f32_e64 v106, -v103, 0
	v_mul_f32_e64 v103, |v103|, s0
	v_exp_f32_e32 v103, v103
	s_nop 0
	v_add_f32_e32 v103, 1.0, v103
	v_cmp_gt_f32_e32 vcc, s31, v103
	s_nop 1
	v_cndmask_b32_e64 v107, 0, 32, vcc
	v_ldexp_f32 v103, v103, v107
	v_log_f32_e32 v103, v103
	s_nop 0
	v_mul_f32_e32 v107, 0x3f317217, v103
	v_fma_f32 v107, v103, s1, -v107
	v_fmac_f32_e32 v107, 0x3377d1cf, v103
	v_fmac_f32_e32 v107, 0x3f317217, v103
	v_cmp_lt_f32_e64 s[42:43], |v103|, s33
	s_nop 1
	v_cndmask_b32_e64 v103, v103, v107, s[42:43]
	v_cndmask_b32_e32 v107, 0, v199, vcc
	v_sub_f32_e32 v103, v103, v107
	v_add_f32_e32 v103, v106, v103
	v_sub_f32_e32 v103, -0.5, v103
	v_mul_f32_e32 v103, 0x3fb8aa3b, v103
	v_exp_f32_e32 v103, v103
	v_add_u32_e32 v106, v101, v110
	v_mov_b32_e32 v107, v1
	v_lshl_add_u64 v[106:107], v[106:107], 2, s[48:49]
	v_mul_f32_e32 v103, 0xbfb8aa3b, v103
	v_exp_f32_e32 v103, v103
	global_store_dword v[106:107], v103, off
	v_add_f32_e32 v103, v67, v102
	v_max_f32_e64 v106, -v103, 0
	v_mul_f32_e64 v103, |v103|, s0
	v_exp_f32_e32 v103, v103
	s_nop 0
	v_add_f32_e32 v103, 1.0, v103
	v_cmp_gt_f32_e32 vcc, s31, v103
	s_nop 1
	v_cndmask_b32_e64 v107, 0, 32, vcc
	v_ldexp_f32 v103, v103, v107
	v_log_f32_e32 v103, v103
	s_nop 0
	v_mul_f32_e32 v107, 0x3f317217, v103
	v_fma_f32 v107, v103, s1, -v107
	v_fmac_f32_e32 v107, 0x3377d1cf, v103
	v_fmac_f32_e32 v107, 0x3f317217, v103
	v_cmp_lt_f32_e64 s[42:43], |v103|, s33
	s_nop 1
	v_cndmask_b32_e64 v103, v103, v107, s[42:43]
	v_cndmask_b32_e32 v107, 0, v199, vcc
	v_sub_f32_e32 v103, v103, v107
	v_add_f32_e32 v103, v106, v103
	v_sub_f32_e32 v103, -0.5, v103
	v_mul_f32_e32 v103, 0x3fb8aa3b, v103
	v_exp_f32_e32 v103, v103
	v_add_u32_e32 v106, v101, v159
	v_mov_b32_e32 v107, v1
	v_lshl_add_u64 v[106:107], v[106:107], 2, s[48:49]
	v_mul_f32_e32 v103, 0xbfb8aa3b, v103
	v_exp_f32_e32 v103, v103
	global_store_dword v[106:107], v103, off
	v_add_f32_e32 v103, v68, v102
	v_max_f32_e64 v106, -v103, 0
	v_mul_f32_e64 v103, |v103|, s0
	v_exp_f32_e32 v103, v103
	s_nop 0
	v_add_f32_e32 v103, 1.0, v103
	v_cmp_gt_f32_e32 vcc, s31, v103
	s_nop 1
	v_cndmask_b32_e64 v107, 0, 32, vcc
	v_ldexp_f32 v103, v103, v107
	v_log_f32_e32 v103, v103
	s_nop 0
	v_mul_f32_e32 v107, 0x3f317217, v103
	v_fma_f32 v107, v103, s1, -v107
	v_fmac_f32_e32 v107, 0x3377d1cf, v103
	v_fmac_f32_e32 v107, 0x3f317217, v103
	v_cmp_lt_f32_e64 s[42:43], |v103|, s33
	s_nop 1
	v_cndmask_b32_e64 v103, v103, v107, s[42:43]
	v_cndmask_b32_e32 v107, 0, v199, vcc
	v_sub_f32_e32 v103, v103, v107
	v_add_f32_e32 v103, v106, v103
	v_sub_f32_e32 v103, -0.5, v103
	v_mul_f32_e32 v103, 0x3fb8aa3b, v103
	v_exp_f32_e32 v103, v103
	v_add_u32_e32 v106, v101, v158
	v_mov_b32_e32 v107, v1
	v_lshl_add_u64 v[106:107], v[106:107], 2, s[48:49]
	v_mul_f32_e32 v103, 0xbfb8aa3b, v103
	v_exp_f32_e32 v103, v103
	global_store_dword v[106:107], v103, off
	v_add_f32_e32 v103, v69, v102
	v_max_f32_e64 v106, -v103, 0
	v_mul_f32_e64 v103, |v103|, s0
	v_exp_f32_e32 v103, v103
	s_nop 0
	v_add_f32_e32 v103, 1.0, v103
	v_cmp_gt_f32_e32 vcc, s31, v103
	s_nop 1
	v_cndmask_b32_e64 v107, 0, 32, vcc
	v_ldexp_f32 v103, v103, v107
	v_log_f32_e32 v103, v103
	s_nop 0
	v_mul_f32_e32 v107, 0x3f317217, v103
	v_fma_f32 v107, v103, s1, -v107
	v_fmac_f32_e32 v107, 0x3377d1cf, v103
	v_fmac_f32_e32 v107, 0x3f317217, v103
	v_cmp_lt_f32_e64 s[42:43], |v103|, s33
	s_nop 1
	v_cndmask_b32_e64 v103, v103, v107, s[42:43]
	v_cndmask_b32_e32 v107, 0, v199, vcc
	v_sub_f32_e32 v103, v103, v107
	v_add_f32_e32 v103, v106, v103
	v_sub_f32_e32 v103, -0.5, v103
	v_mul_f32_e32 v103, 0x3fb8aa3b, v103
	v_exp_f32_e32 v103, v103
	v_add_u32_e32 v106, v101, v157
	v_mov_b32_e32 v107, v1
	v_lshl_add_u64 v[106:107], v[106:107], 2, s[48:49]
	v_mul_f32_e32 v103, 0xbfb8aa3b, v103
	v_exp_f32_e32 v103, v103
	global_store_dword v[106:107], v103, off
	v_add_f32_e32 v103, v70, v102
	v_max_f32_e64 v106, -v103, 0
	v_mul_f32_e64 v103, |v103|, s0
	v_exp_f32_e32 v103, v103
	s_nop 0
	v_add_f32_e32 v103, 1.0, v103
	v_cmp_gt_f32_e32 vcc, s31, v103
	s_nop 1
	v_cndmask_b32_e64 v107, 0, 32, vcc
	v_ldexp_f32 v103, v103, v107
	v_log_f32_e32 v103, v103
	s_nop 0
	v_mul_f32_e32 v107, 0x3f317217, v103
	v_fma_f32 v107, v103, s1, -v107
	v_fmac_f32_e32 v107, 0x3377d1cf, v103
	v_fmac_f32_e32 v107, 0x3f317217, v103
	v_cmp_lt_f32_e64 s[42:43], |v103|, s33
	s_nop 1
	v_cndmask_b32_e64 v103, v103, v107, s[42:43]
	v_cndmask_b32_e32 v107, 0, v199, vcc
	v_sub_f32_e32 v103, v103, v107
	v_add_f32_e32 v103, v106, v103
	v_sub_f32_e32 v103, -0.5, v103
	v_mul_f32_e32 v103, 0x3fb8aa3b, v103
	v_exp_f32_e32 v103, v103
	v_add_u32_e32 v106, v101, v156
	v_mov_b32_e32 v107, v1
	v_lshl_add_u64 v[106:107], v[106:107], 2, s[48:49]
	v_mul_f32_e32 v103, 0xbfb8aa3b, v103
	v_exp_f32_e32 v103, v103
	global_store_dword v[106:107], v103, off
	v_add_f32_e32 v103, v71, v102
	v_max_f32_e64 v106, -v103, 0
	v_mul_f32_e64 v103, |v103|, s0
	v_exp_f32_e32 v103, v103
	s_nop 0
	v_add_f32_e32 v103, 1.0, v103
	v_cmp_gt_f32_e32 vcc, s31, v103
	s_nop 1
	v_cndmask_b32_e64 v107, 0, 32, vcc
	v_ldexp_f32 v103, v103, v107
	v_log_f32_e32 v103, v103
	s_nop 0
	v_mul_f32_e32 v107, 0x3f317217, v103
	v_fma_f32 v107, v103, s1, -v107
	v_fmac_f32_e32 v107, 0x3377d1cf, v103
	v_fmac_f32_e32 v107, 0x3f317217, v103
	v_cmp_lt_f32_e64 s[42:43], |v103|, s33
	s_nop 1
	v_cndmask_b32_e64 v103, v103, v107, s[42:43]
	v_cndmask_b32_e32 v107, 0, v199, vcc
	v_sub_f32_e32 v103, v103, v107
	v_add_f32_e32 v103, v106, v103
	v_sub_f32_e32 v103, -0.5, v103
	v_mul_f32_e32 v103, 0x3fb8aa3b, v103
	v_exp_f32_e32 v103, v103
	v_add_u32_e32 v106, v101, v155
	v_mov_b32_e32 v107, v1
	v_lshl_add_u64 v[106:107], v[106:107], 2, s[48:49]
	v_mul_f32_e32 v103, 0xbfb8aa3b, v103
	v_exp_f32_e32 v103, v103
	global_store_dword v[106:107], v103, off
	v_add_f32_e32 v103, v72, v102
	v_max_f32_e64 v106, -v103, 0
	v_mul_f32_e64 v103, |v103|, s0
	v_exp_f32_e32 v103, v103
	s_nop 0
	v_add_f32_e32 v103, 1.0, v103
	v_cmp_gt_f32_e32 vcc, s31, v103
	s_nop 1
	v_cndmask_b32_e64 v107, 0, 32, vcc
	v_ldexp_f32 v103, v103, v107
	v_log_f32_e32 v103, v103
	s_nop 0
	v_mul_f32_e32 v107, 0x3f317217, v103
	v_fma_f32 v107, v103, s1, -v107
	v_fmac_f32_e32 v107, 0x3377d1cf, v103
	v_fmac_f32_e32 v107, 0x3f317217, v103
	v_cmp_lt_f32_e64 s[42:43], |v103|, s33
	s_nop 1
	v_cndmask_b32_e64 v103, v103, v107, s[42:43]
	v_cndmask_b32_e32 v107, 0, v199, vcc
	v_sub_f32_e32 v103, v103, v107
	v_add_f32_e32 v103, v106, v103
	v_sub_f32_e32 v103, -0.5, v103
	v_mul_f32_e32 v103, 0x3fb8aa3b, v103
	v_exp_f32_e32 v103, v103
	v_add_u32_e32 v106, v101, v154
	v_mov_b32_e32 v107, v1
	v_lshl_add_u64 v[106:107], v[106:107], 2, s[48:49]
	v_mul_f32_e32 v103, 0xbfb8aa3b, v103
	v_exp_f32_e32 v103, v103
	global_store_dword v[106:107], v103, off
	v_add_f32_e32 v103, v73, v102
	v_max_f32_e64 v106, -v103, 0
	v_mul_f32_e64 v103, |v103|, s0
	v_exp_f32_e32 v103, v103
	s_nop 0
	v_add_f32_e32 v103, 1.0, v103
	v_cmp_gt_f32_e32 vcc, s31, v103
	s_nop 1
	v_cndmask_b32_e64 v107, 0, 32, vcc
	v_ldexp_f32 v103, v103, v107
	v_log_f32_e32 v103, v103
	s_nop 0
	v_mul_f32_e32 v107, 0x3f317217, v103
	v_fma_f32 v107, v103, s1, -v107
	v_fmac_f32_e32 v107, 0x3377d1cf, v103
	v_fmac_f32_e32 v107, 0x3f317217, v103
	v_cmp_lt_f32_e64 s[42:43], |v103|, s33
	s_nop 1
	v_cndmask_b32_e64 v103, v103, v107, s[42:43]
	v_cndmask_b32_e32 v107, 0, v199, vcc
	v_sub_f32_e32 v103, v103, v107
	v_add_f32_e32 v103, v106, v103
	v_sub_f32_e32 v103, -0.5, v103
	v_mul_f32_e32 v103, 0x3fb8aa3b, v103
	v_exp_f32_e32 v103, v103
	v_add_u32_e32 v106, v101, v153
	v_mov_b32_e32 v107, v1
	v_lshl_add_u64 v[106:107], v[106:107], 2, s[48:49]
	v_mul_f32_e32 v103, 0xbfb8aa3b, v103
	v_exp_f32_e32 v103, v103
	global_store_dword v[106:107], v103, off
	v_add_f32_e32 v103, v74, v102
	v_max_f32_e64 v106, -v103, 0
	v_mul_f32_e64 v103, |v103|, s0
	v_exp_f32_e32 v103, v103
	s_nop 0
	v_add_f32_e32 v103, 1.0, v103
	v_cmp_gt_f32_e32 vcc, s31, v103
	s_nop 1
	v_cndmask_b32_e64 v107, 0, 32, vcc
	v_ldexp_f32 v103, v103, v107
	v_log_f32_e32 v103, v103
	s_nop 0
	v_mul_f32_e32 v107, 0x3f317217, v103
	v_fma_f32 v107, v103, s1, -v107
	v_fmac_f32_e32 v107, 0x3377d1cf, v103
	v_fmac_f32_e32 v107, 0x3f317217, v103
	v_cmp_lt_f32_e64 s[42:43], |v103|, s33
	s_nop 1
	v_cndmask_b32_e64 v103, v103, v107, s[42:43]
	v_cndmask_b32_e32 v107, 0, v199, vcc
	v_sub_f32_e32 v103, v103, v107
	v_add_f32_e32 v103, v106, v103
	v_sub_f32_e32 v103, -0.5, v103
	v_mul_f32_e32 v103, 0x3fb8aa3b, v103
	v_exp_f32_e32 v103, v103
	v_add_u32_e32 v106, v101, v152
	v_mov_b32_e32 v107, v1
	v_lshl_add_u64 v[106:107], v[106:107], 2, s[48:49]
	v_mul_f32_e32 v103, 0xbfb8aa3b, v103
	v_exp_f32_e32 v103, v103
	global_store_dword v[106:107], v103, off
	v_add_f32_e32 v103, v75, v102
	v_max_f32_e64 v106, -v103, 0
	v_mul_f32_e64 v103, |v103|, s0
	v_exp_f32_e32 v103, v103
	s_nop 0
	v_add_f32_e32 v103, 1.0, v103
	v_cmp_gt_f32_e32 vcc, s31, v103
	s_nop 1
	v_cndmask_b32_e64 v107, 0, 32, vcc
	v_ldexp_f32 v103, v103, v107
	v_log_f32_e32 v103, v103
	s_nop 0
	v_mul_f32_e32 v107, 0x3f317217, v103
	v_fma_f32 v107, v103, s1, -v107
	v_fmac_f32_e32 v107, 0x3377d1cf, v103
	v_fmac_f32_e32 v107, 0x3f317217, v103
	v_cmp_lt_f32_e64 s[42:43], |v103|, s33
	s_nop 1
	v_cndmask_b32_e64 v103, v103, v107, s[42:43]
	v_cndmask_b32_e32 v107, 0, v199, vcc
	v_sub_f32_e32 v103, v103, v107
	v_add_f32_e32 v103, v106, v103
	v_sub_f32_e32 v103, -0.5, v103
	v_mul_f32_e32 v103, 0x3fb8aa3b, v103
	v_exp_f32_e32 v103, v103
	v_add_u32_e32 v106, v101, v151
	v_mov_b32_e32 v107, v1
	v_lshl_add_u64 v[106:107], v[106:107], 2, s[48:49]
	v_mul_f32_e32 v103, 0xbfb8aa3b, v103
	v_exp_f32_e32 v103, v103
	global_store_dword v[106:107], v103, off
	v_add_f32_e32 v103, v76, v102
	v_max_f32_e64 v106, -v103, 0
	v_mul_f32_e64 v103, |v103|, s0
	v_exp_f32_e32 v103, v103
	s_nop 0
	v_add_f32_e32 v103, 1.0, v103
	v_cmp_gt_f32_e32 vcc, s31, v103
	s_nop 1
	v_cndmask_b32_e64 v107, 0, 32, vcc
	v_ldexp_f32 v103, v103, v107
	v_log_f32_e32 v103, v103
	s_nop 0
	v_mul_f32_e32 v107, 0x3f317217, v103
	v_fma_f32 v107, v103, s1, -v107
	v_fmac_f32_e32 v107, 0x3377d1cf, v103
	v_fmac_f32_e32 v107, 0x3f317217, v103
	v_cmp_lt_f32_e64 s[42:43], |v103|, s33
	s_nop 1
	v_cndmask_b32_e64 v103, v103, v107, s[42:43]
	v_cndmask_b32_e32 v107, 0, v199, vcc
	v_sub_f32_e32 v103, v103, v107
	v_add_f32_e32 v103, v106, v103
	v_sub_f32_e32 v103, -0.5, v103
	v_mul_f32_e32 v103, 0x3fb8aa3b, v103
	v_exp_f32_e32 v103, v103
	v_add_u32_e32 v106, v101, v150
	v_mov_b32_e32 v107, v1
	v_lshl_add_u64 v[106:107], v[106:107], 2, s[48:49]
	v_mul_f32_e32 v103, 0xbfb8aa3b, v103
	v_exp_f32_e32 v103, v103
	global_store_dword v[106:107], v103, off
	v_add_f32_e32 v103, v77, v102
	v_max_f32_e64 v106, -v103, 0
	v_mul_f32_e64 v103, |v103|, s0
	v_exp_f32_e32 v103, v103
	s_nop 0
	v_add_f32_e32 v103, 1.0, v103
	v_cmp_gt_f32_e32 vcc, s31, v103
	s_nop 1
	v_cndmask_b32_e64 v107, 0, 32, vcc
	v_ldexp_f32 v103, v103, v107
	v_log_f32_e32 v103, v103
	s_nop 0
	v_mul_f32_e32 v107, 0x3f317217, v103
	v_fma_f32 v107, v103, s1, -v107
	v_fmac_f32_e32 v107, 0x3377d1cf, v103
	v_fmac_f32_e32 v107, 0x3f317217, v103
	v_cmp_lt_f32_e64 s[42:43], |v103|, s33
	s_nop 1
	v_cndmask_b32_e64 v103, v103, v107, s[42:43]
	v_cndmask_b32_e32 v107, 0, v199, vcc
	v_sub_f32_e32 v103, v103, v107
	v_add_f32_e32 v103, v106, v103
	v_sub_f32_e32 v103, -0.5, v103
	v_mul_f32_e32 v103, 0x3fb8aa3b, v103
	v_exp_f32_e32 v103, v103
	v_add_u32_e32 v106, v101, v149
	v_mov_b32_e32 v107, v1
	v_lshl_add_u64 v[106:107], v[106:107], 2, s[48:49]
	v_mul_f32_e32 v103, 0xbfb8aa3b, v103
	v_exp_f32_e32 v103, v103
	global_store_dword v[106:107], v103, off
	v_add_f32_e32 v103, v78, v102
	v_max_f32_e64 v106, -v103, 0
	v_mul_f32_e64 v103, |v103|, s0
	v_exp_f32_e32 v103, v103
	s_nop 0
	v_add_f32_e32 v103, 1.0, v103
	v_cmp_gt_f32_e32 vcc, s31, v103
	s_nop 1
	v_cndmask_b32_e64 v107, 0, 32, vcc
	v_ldexp_f32 v103, v103, v107
	v_log_f32_e32 v103, v103
	s_nop 0
	v_mul_f32_e32 v107, 0x3f317217, v103
	v_fma_f32 v107, v103, s1, -v107
	v_fmac_f32_e32 v107, 0x3377d1cf, v103
	v_fmac_f32_e32 v107, 0x3f317217, v103
	v_cmp_lt_f32_e64 s[42:43], |v103|, s33
	s_nop 1
	v_cndmask_b32_e64 v103, v103, v107, s[42:43]
	v_cndmask_b32_e32 v107, 0, v199, vcc
	v_sub_f32_e32 v103, v103, v107
	v_add_f32_e32 v103, v106, v103
	v_sub_f32_e32 v103, -0.5, v103
	v_mul_f32_e32 v103, 0x3fb8aa3b, v103
	v_exp_f32_e32 v103, v103
	v_add_u32_e32 v106, v101, v148
	v_mov_b32_e32 v107, v1
	v_lshl_add_u64 v[106:107], v[106:107], 2, s[48:49]
	v_mul_f32_e32 v103, 0xbfb8aa3b, v103
	v_exp_f32_e32 v103, v103
	global_store_dword v[106:107], v103, off
	v_add_f32_e32 v103, v79, v102
	v_max_f32_e64 v106, -v103, 0
	v_mul_f32_e64 v103, |v103|, s0
	v_exp_f32_e32 v103, v103
	s_nop 0
	v_add_f32_e32 v103, 1.0, v103
	v_cmp_gt_f32_e32 vcc, s31, v103
	s_nop 1
	v_cndmask_b32_e64 v107, 0, 32, vcc
	v_ldexp_f32 v103, v103, v107
	v_log_f32_e32 v103, v103
	s_nop 0
	v_mul_f32_e32 v107, 0x3f317217, v103
	v_fma_f32 v107, v103, s1, -v107
	v_fmac_f32_e32 v107, 0x3377d1cf, v103
	v_fmac_f32_e32 v107, 0x3f317217, v103
	v_cmp_lt_f32_e64 s[42:43], |v103|, s33
	s_nop 1
	v_cndmask_b32_e64 v103, v103, v107, s[42:43]
	v_cndmask_b32_e32 v107, 0, v199, vcc
	v_sub_f32_e32 v103, v103, v107
	v_add_f32_e32 v103, v106, v103
	v_sub_f32_e32 v103, -0.5, v103
	v_mul_f32_e32 v103, 0x3fb8aa3b, v103
	v_exp_f32_e32 v103, v103
	v_add_u32_e32 v106, v101, v113
	v_mov_b32_e32 v107, v1
	v_lshl_add_u64 v[106:107], v[106:107], 2, s[48:49]
	v_mul_f32_e32 v103, 0xbfb8aa3b, v103
	v_exp_f32_e32 v103, v103
	global_store_dword v[106:107], v103, off
	v_add_f32_e32 v103, v80, v102
	v_max_f32_e64 v106, -v103, 0
	v_mul_f32_e64 v103, |v103|, s0
	v_exp_f32_e32 v103, v103
	v_add_f32_e32 v102, v81, v102
	v_add_f32_e32 v103, 1.0, v103
	v_cmp_gt_f32_e32 vcc, s31, v103
	s_nop 1
	v_cndmask_b32_e64 v107, 0, 32, vcc
	v_ldexp_f32 v103, v103, v107
	v_log_f32_e32 v103, v103
	s_nop 0
	v_mul_f32_e32 v107, 0x3f317217, v103
	v_fma_f32 v107, v103, s1, -v107
	v_fmac_f32_e32 v107, 0x3377d1cf, v103
	v_fmac_f32_e32 v107, 0x3f317217, v103
	v_cmp_lt_f32_e64 s[42:43], |v103|, s33
	s_nop 1
	v_cndmask_b32_e64 v103, v103, v107, s[42:43]
	v_cndmask_b32_e32 v107, 0, v199, vcc
	v_sub_f32_e32 v103, v103, v107
	v_add_f32_e32 v103, v106, v103
	v_sub_f32_e32 v103, -0.5, v103
	v_mul_f32_e32 v103, 0x3fb8aa3b, v103
	v_exp_f32_e32 v103, v103
	v_add_u32_e32 v106, v101, v112
	v_mov_b32_e32 v107, v1
	v_lshl_add_u64 v[106:107], v[106:107], 2, s[48:49]
	v_mul_f32_e32 v103, 0xbfb8aa3b, v103
	v_exp_f32_e32 v103, v103
	global_store_dword v[106:107], v103, off
	v_max_f32_e64 v103, -v102, 0
	v_mul_f32_e64 v102, |v102|, s0
	v_exp_f32_e32 v102, v102
	s_nop 0
	v_add_f32_e32 v102, 1.0, v102
	v_cmp_gt_f32_e32 vcc, s31, v102
	s_nop 1
	v_cndmask_b32_e64 v106, 0, 32, vcc
	v_ldexp_f32 v102, v102, v106
	v_log_f32_e32 v102, v102
	s_nop 0
	v_mul_f32_e32 v106, 0x3f317217, v102
	v_fma_f32 v106, v102, s1, -v106
	v_fmac_f32_e32 v106, 0x3377d1cf, v102
	v_fmac_f32_e32 v106, 0x3f317217, v102
	v_cmp_lt_f32_e64 s[42:43], |v102|, s33
	s_nop 1
	v_cndmask_b32_e64 v102, v102, v106, s[42:43]
	v_cndmask_b32_e32 v106, 0, v199, vcc
	v_sub_f32_e32 v102, v102, v106
	v_add_f32_e32 v102, v103, v102
	v_sub_f32_e32 v102, -0.5, v102
	v_mul_f32_e32 v102, 0x3fb8aa3b, v102
	v_exp_f32_e32 v102, v102
	v_mov_b32_e32 v103, v1
	v_mul_f32_e32 v102, 0xbfb8aa3b, v102
	v_exp_f32_e32 v106, v102
	v_add_u32_e32 v102, v101, v111
	v_lshl_add_u64 v[102:103], v[102:103], 2, s[48:49]
	global_store_dword v[102:103], v106, off
	v_mov_b32_e32 v111, v236
	v_add_f32_e32 v102, v50, v111
	v_mul_f32_e64 v103, |v102|, s0
	v_exp_f32_e32 v103, v103
	v_max_f32_e64 v102, -v102, 0
	v_add_f32_e32 v106, v51, v111
	v_add_u32_e32 v157, 0x4000, v110
	v_add_f32_e32 v103, 1.0, v103
	v_cmp_gt_f32_e32 vcc, s31, v103
	v_add_u32_e32 v156, 0x4200, v110
	v_add_u32_e32 v155, 0x4400, v110
	v_cndmask_b32_e64 v107, 0, 32, vcc
	v_ldexp_f32 v103, v103, v107
	v_log_f32_e32 v103, v103
	v_cndmask_b32_e32 v112, 0, v199, vcc
	v_mul_f32_e64 v107, |v106|, s0
	v_max_f32_e64 v106, -v106, 0
	v_mul_f32_e32 v113, 0x3f317217, v103
	v_fma_f32 v113, v103, s1, -v113
	v_fmac_f32_e32 v113, 0x3377d1cf, v103
	v_fmac_f32_e32 v113, 0x3f317217, v103
	v_cmp_lt_f32_e64 vcc, |v103|, s33
	v_add_u32_e32 v153, 0x4600, v110
	s_nop 0
	v_cndmask_b32_e32 v103, v103, v113, vcc
	v_sub_f32_e32 v103, v103, v112
	v_add_f32_e32 v102, v102, v103
	v_sub_f32_e32 v102, -0.5, v102
	v_mul_f32_e32 v102, 0x3fb8aa3b, v102
	v_exp_f32_e32 v103, v107
	v_exp_f32_e32 v102, v102
	v_add_f32_e32 v103, 1.0, v103
	v_mul_f32_e32 v102, 0xbfb8aa3b, v102
	v_cmp_gt_f32_e32 vcc, s31, v103
	v_exp_f32_e32 v107, v102
	s_nop 0
	v_cndmask_b32_e64 v102, 0, 32, vcc
	v_ldexp_f32 v102, v103, v102
	v_log_f32_e32 v103, v102
	v_add_u32_e32 v102, v100, v157
	v_mul_f32_e32 v112, 0x3f317217, v103
	v_fma_f32 v112, v103, s1, -v112
	v_fmac_f32_e32 v112, 0x3377d1cf, v103
	v_fmac_f32_e32 v112, 0x3f317217, v103
	v_cmp_lt_f32_e64 s[42:43], |v103|, s33
	s_nop 1
	v_cndmask_b32_e64 v103, v103, v112, s[42:43]
	v_cndmask_b32_e32 v112, 0, v199, vcc
	v_sub_f32_e32 v103, v103, v112
	v_add_f32_e32 v103, v106, v103
	v_sub_f32_e32 v103, -0.5, v103
	v_mul_f32_e32 v103, 0x3fb8aa3b, v103
	v_exp_f32_e32 v106, v103
	v_mov_b32_e32 v103, v1
	v_lshl_add_u64 v[102:103], v[102:103], 2, s[48:49]
	global_store_dword v[102:103], v107, off
	v_mul_f32_e32 v102, 0xbfb8aa3b, v106
	v_add_f32_e32 v106, v52, v111
	v_mul_f32_e64 v103, |v106|, s0
	v_exp_f32_e32 v103, v103
	v_max_f32_e64 v106, -v106, 0
	v_exp_f32_e32 v107, v102
	v_add_u32_e32 v102, v100, v156
	v_add_f32_e32 v103, 1.0, v103
	v_cmp_gt_f32_e32 vcc, s31, v103
	s_nop 1
	v_cndmask_b32_e64 v112, 0, 32, vcc
	v_ldexp_f32 v103, v103, v112
	v_log_f32_e32 v112, v103
	v_mov_b32_e32 v103, v1
	v_lshl_add_u64 v[102:103], v[102:103], 2, s[48:49]
	global_store_dword v[102:103], v107, off
	v_mul_f32_e32 v113, 0x3f317217, v112
	v_fma_f32 v113, v112, s1, -v113
	v_fmac_f32_e32 v113, 0x3377d1cf, v112
	v_fmac_f32_e32 v113, 0x3f317217, v112
	v_cmp_lt_f32_e64 s[42:43], |v112|, s33
	s_nop 1
	v_cndmask_b32_e64 v112, v112, v113, s[42:43]
	v_cndmask_b32_e32 v113, 0, v199, vcc
	v_sub_f32_e32 v112, v112, v113
	v_add_f32_e32 v106, v106, v112
	v_sub_f32_e32 v106, -0.5, v106
	v_mul_f32_e32 v106, 0x3fb8aa3b, v106
	v_add_f32_e32 v112, v53, v111
	v_exp_f32_e32 v106, v106
	v_mul_f32_e64 v113, |v112|, s0
	v_exp_f32_e32 v113, v113
	v_max_f32_e64 v107, -v112, 0
	v_mul_f32_e32 v102, 0xbfb8aa3b, v106
	v_exp_f32_e32 v106, v102
	v_add_f32_e32 v102, 1.0, v113
	v_cmp_gt_f32_e32 vcc, s31, v102
	s_nop 1
	v_cndmask_b32_e64 v103, 0, 32, vcc
	v_ldexp_f32 v102, v102, v103
	v_log_f32_e32 v103, v102
	v_add_u32_e32 v102, v100, v155
	v_mul_f32_e32 v112, 0x3f317217, v103
	v_fma_f32 v112, v103, s1, -v112
	v_fmac_f32_e32 v112, 0x3377d1cf, v103
	v_fmac_f32_e32 v112, 0x3f317217, v103
	v_cmp_lt_f32_e64 s[42:43], |v103|, s33
	s_nop 1
	v_cndmask_b32_e64 v103, v103, v112, s[42:43]
	v_cndmask_b32_e32 v112, 0, v199, vcc
	v_sub_f32_e32 v103, v103, v112
	v_add_f32_e32 v103, v107, v103
	v_sub_f32_e32 v103, -0.5, v103
	v_mul_f32_e32 v103, 0x3fb8aa3b, v103
	v_exp_f32_e32 v107, v103
	v_mov_b32_e32 v103, v1
	v_lshl_add_u64 v[102:103], v[102:103], 2, s[48:49]
	global_store_dword v[102:103], v106, off
	v_mul_f32_e32 v102, 0xbfb8aa3b, v107
	v_exp_f32_e32 v106, v102
	v_add_u32_e32 v102, v100, v153
	v_mov_b32_e32 v103, v1
	v_lshl_add_u64 v[102:103], v[102:103], 2, s[48:49]
	global_store_dword v[102:103], v106, off
	v_add_f32_e32 v102, v54, v111
	v_mul_f32_e64 v103, |v102|, s0
	v_exp_f32_e32 v103, v103
	v_max_f32_e64 v102, -v102, 0
	v_add_f32_e32 v106, v55, v111
	v_add_u32_e32 v154, 0x5000, v110
	v_add_f32_e32 v103, 1.0, v103
	v_cmp_gt_f32_e32 vcc, s31, v103
	v_add_u32_e32 v152, 0x5200, v110
	v_add_u32_e32 v151, 0x5400, v110
	v_cndmask_b32_e64 v107, 0, 32, vcc
	v_ldexp_f32 v103, v103, v107
	v_log_f32_e32 v103, v103
	v_cndmask_b32_e32 v112, 0, v199, vcc
	v_mul_f32_e64 v107, |v106|, s0
	v_max_f32_e64 v106, -v106, 0
	v_mul_f32_e32 v113, 0x3f317217, v103
	v_fma_f32 v113, v103, s1, -v113
	v_fmac_f32_e32 v113, 0x3377d1cf, v103
	v_fmac_f32_e32 v113, 0x3f317217, v103
	v_cmp_lt_f32_e64 vcc, |v103|, s33
	v_add_u32_e32 v149, 0x5600, v110
	s_nop 0
	v_cndmask_b32_e32 v103, v103, v113, vcc
	v_sub_f32_e32 v103, v103, v112
	v_add_f32_e32 v102, v102, v103
	v_sub_f32_e32 v102, -0.5, v102
	v_mul_f32_e32 v102, 0x3fb8aa3b, v102
	v_exp_f32_e32 v103, v107
	v_exp_f32_e32 v102, v102
	v_add_f32_e32 v103, 1.0, v103
	v_mul_f32_e32 v102, 0xbfb8aa3b, v102
	v_cmp_gt_f32_e32 vcc, s31, v103
	v_exp_f32_e32 v107, v102
	s_nop 0
	v_cndmask_b32_e64 v102, 0, 32, vcc
	v_ldexp_f32 v102, v103, v102
	v_log_f32_e32 v103, v102
	v_add_u32_e32 v102, v100, v154
	v_mul_f32_e32 v112, 0x3f317217, v103
	v_fma_f32 v112, v103, s1, -v112
	v_fmac_f32_e32 v112, 0x3377d1cf, v103
	v_fmac_f32_e32 v112, 0x3f317217, v103
	v_cmp_lt_f32_e64 s[42:43], |v103|, s33
	s_nop 1
	v_cndmask_b32_e64 v103, v103, v112, s[42:43]
	v_cndmask_b32_e32 v112, 0, v199, vcc
	v_sub_f32_e32 v103, v103, v112
	v_add_f32_e32 v103, v106, v103
	v_sub_f32_e32 v103, -0.5, v103
	v_mul_f32_e32 v103, 0x3fb8aa3b, v103
	v_exp_f32_e32 v106, v103
	v_mov_b32_e32 v103, v1
	v_lshl_add_u64 v[102:103], v[102:103], 2, s[48:49]
	global_store_dword v[102:103], v107, off
	v_mul_f32_e32 v102, 0xbfb8aa3b, v106
	v_add_f32_e32 v106, v56, v111
	v_mul_f32_e64 v103, |v106|, s0
	v_exp_f32_e32 v103, v103
	v_max_f32_e64 v106, -v106, 0
	v_exp_f32_e32 v107, v102
	v_add_u32_e32 v102, v100, v152
	v_add_f32_e32 v103, 1.0, v103
	v_cmp_gt_f32_e32 vcc, s31, v103
	s_nop 1
	v_cndmask_b32_e64 v112, 0, 32, vcc
	v_ldexp_f32 v103, v103, v112
	v_log_f32_e32 v112, v103
	v_mov_b32_e32 v103, v1
	v_lshl_add_u64 v[102:103], v[102:103], 2, s[48:49]
	global_store_dword v[102:103], v107, off
	v_mul_f32_e32 v113, 0x3f317217, v112
	v_fma_f32 v113, v112, s1, -v113
	v_fmac_f32_e32 v113, 0x3377d1cf, v112
	v_fmac_f32_e32 v113, 0x3f317217, v112
	v_cmp_lt_f32_e64 s[42:43], |v112|, s33
	s_nop 1
	v_cndmask_b32_e64 v112, v112, v113, s[42:43]
	v_cndmask_b32_e32 v113, 0, v199, vcc
	v_sub_f32_e32 v112, v112, v113
	v_add_f32_e32 v106, v106, v112
	v_sub_f32_e32 v106, -0.5, v106
	v_mul_f32_e32 v106, 0x3fb8aa3b, v106
	v_add_f32_e32 v112, v57, v111
	v_exp_f32_e32 v106, v106
	v_mul_f32_e64 v113, |v112|, s0
	v_exp_f32_e32 v113, v113
	v_max_f32_e64 v107, -v112, 0
	v_mul_f32_e32 v102, 0xbfb8aa3b, v106
	v_exp_f32_e32 v106, v102
	v_add_f32_e32 v102, 1.0, v113
	v_cmp_gt_f32_e32 vcc, s31, v102
	s_nop 1
	v_cndmask_b32_e64 v103, 0, 32, vcc
	v_ldexp_f32 v102, v102, v103
	v_log_f32_e32 v103, v102
	v_add_u32_e32 v102, v100, v151
	v_mul_f32_e32 v112, 0x3f317217, v103
	v_fma_f32 v112, v103, s1, -v112
	v_fmac_f32_e32 v112, 0x3377d1cf, v103
	v_fmac_f32_e32 v112, 0x3f317217, v103
	v_cmp_lt_f32_e64 s[42:43], |v103|, s33
	s_nop 1
	v_cndmask_b32_e64 v103, v103, v112, s[42:43]
	v_cndmask_b32_e32 v112, 0, v199, vcc
	v_sub_f32_e32 v103, v103, v112
	v_add_f32_e32 v103, v107, v103
	v_sub_f32_e32 v103, -0.5, v103
	v_mul_f32_e32 v103, 0x3fb8aa3b, v103
	v_exp_f32_e32 v107, v103
	v_mov_b32_e32 v103, v1
	v_lshl_add_u64 v[102:103], v[102:103], 2, s[48:49]
	global_store_dword v[102:103], v106, off
	v_mul_f32_e32 v102, 0xbfb8aa3b, v107
	v_exp_f32_e32 v106, v102
	v_add_u32_e32 v102, v100, v149
	v_mov_b32_e32 v103, v1
	v_lshl_add_u64 v[102:103], v[102:103], 2, s[48:49]
	global_store_dword v[102:103], v106, off
	v_add_f32_e32 v102, v58, v111
	v_mul_f32_e64 v103, |v102|, s0
	v_exp_f32_e32 v103, v103
	v_max_f32_e64 v102, -v102, 0
	v_add_f32_e32 v106, v59, v111
	v_add_u32_e32 v150, 0x6000, v110
	v_add_f32_e32 v103, 1.0, v103
	v_cmp_gt_f32_e32 vcc, s31, v103
	v_add_u32_e32 v148, 0x6200, v110
	s_nop 0
	v_cndmask_b32_e64 v107, 0, 32, vcc
	v_ldexp_f32 v103, v103, v107
	v_log_f32_e32 v103, v103
	v_cndmask_b32_e32 v112, 0, v199, vcc
	v_mul_f32_e64 v107, |v106|, s0
	v_max_f32_e64 v106, -v106, 0
	v_mul_f32_e32 v113, 0x3f317217, v103
	v_fma_f32 v113, v103, s1, -v113
	v_fmac_f32_e32 v113, 0x3377d1cf, v103
	v_fmac_f32_e32 v113, 0x3f317217, v103
	v_cmp_lt_f32_e64 vcc, |v103|, s33
	s_nop 1
	v_cndmask_b32_e32 v103, v103, v113, vcc
	v_sub_f32_e32 v103, v103, v112
	v_add_f32_e32 v102, v102, v103
	v_sub_f32_e32 v102, -0.5, v102
	v_mul_f32_e32 v102, 0x3fb8aa3b, v102
	v_exp_f32_e32 v103, v107
	v_exp_f32_e32 v102, v102
	v_add_f32_e32 v103, 1.0, v103
	v_mul_f32_e32 v102, 0xbfb8aa3b, v102
	v_cmp_gt_f32_e32 vcc, s31, v103
	v_exp_f32_e32 v107, v102
	s_nop 0
	v_cndmask_b32_e64 v102, 0, 32, vcc
	v_ldexp_f32 v102, v103, v102
	v_log_f32_e32 v103, v102
	v_add_u32_e32 v102, v100, v150
	v_mul_f32_e32 v112, 0x3f317217, v103
	v_fma_f32 v112, v103, s1, -v112
	v_fmac_f32_e32 v112, 0x3377d1cf, v103
	v_fmac_f32_e32 v112, 0x3f317217, v103
	v_cmp_lt_f32_e64 s[42:43], |v103|, s33
	s_nop 1
	v_cndmask_b32_e64 v103, v103, v112, s[42:43]
	v_cndmask_b32_e32 v112, 0, v199, vcc
	v_sub_f32_e32 v103, v103, v112
	v_add_f32_e32 v103, v106, v103
	v_sub_f32_e32 v103, -0.5, v103
	v_mul_f32_e32 v103, 0x3fb8aa3b, v103
	v_exp_f32_e32 v106, v103
	v_mov_b32_e32 v103, v1
	v_lshl_add_u64 v[102:103], v[102:103], 2, s[48:49]
	global_store_dword v[102:103], v107, off
	v_mul_f32_e32 v102, 0xbfb8aa3b, v106
	v_add_f32_e32 v106, v60, v111
	v_mul_f32_e64 v103, |v106|, s0
	v_exp_f32_e32 v103, v103
	v_max_f32_e64 v106, -v106, 0
	v_exp_f32_e32 v107, v102
	v_add_u32_e32 v102, v100, v148
	v_add_f32_e32 v103, 1.0, v103
	v_cmp_gt_f32_e32 vcc, s31, v103
	s_nop 1
	v_cndmask_b32_e64 v112, 0, 32, vcc
	v_ldexp_f32 v103, v103, v112
	v_log_f32_e32 v112, v103
	v_mov_b32_e32 v103, v1
	v_lshl_add_u64 v[102:103], v[102:103], 2, s[48:49]
	global_store_dword v[102:103], v107, off
	v_mul_f32_e32 v113, 0x3f317217, v112
	v_fma_f32 v113, v112, s1, -v113
	v_fmac_f32_e32 v113, 0x3377d1cf, v112
	v_fmac_f32_e32 v113, 0x3f317217, v112
	v_cmp_lt_f32_e64 s[42:43], |v112|, s33
	s_nop 1
	v_cndmask_b32_e64 v112, v112, v113, s[42:43]
	v_cndmask_b32_e32 v113, 0, v199, vcc
	v_sub_f32_e32 v112, v112, v113
	v_add_f32_e32 v106, v106, v112
	v_sub_f32_e32 v106, -0.5, v106
	v_mul_f32_e32 v106, 0x3fb8aa3b, v106
	v_add_f32_e32 v113, v61, v111
	v_exp_f32_e32 v106, v106
	v_mul_f32_e64 v112, |v113|, s0
	v_exp_f32_e32 v112, v112
	v_max_f32_e64 v107, -v113, 0
	v_mul_f32_e32 v102, 0xbfb8aa3b, v106
	v_exp_f32_e32 v106, v102
	v_add_f32_e32 v102, 1.0, v112
	v_cmp_gt_f32_e32 vcc, s31, v102
	v_add_u32_e32 v112, 0x6400, v110
	s_nop 0
	v_cndmask_b32_e64 v103, 0, 32, vcc
	v_ldexp_f32 v102, v102, v103
	v_log_f32_e32 v103, v102
	v_add_u32_e32 v102, v100, v112
	v_mul_f32_e32 v113, 0x3f317217, v103
	v_fma_f32 v113, v103, s1, -v113
	v_fmac_f32_e32 v113, 0x3377d1cf, v103
	v_fmac_f32_e32 v113, 0x3f317217, v103
	v_cmp_lt_f32_e64 s[42:43], |v103|, s33
	s_nop 1
	v_cndmask_b32_e64 v103, v103, v113, s[42:43]
	v_cndmask_b32_e32 v113, 0, v199, vcc
	v_sub_f32_e32 v103, v103, v113
	v_add_f32_e32 v103, v107, v103
	v_sub_f32_e32 v103, -0.5, v103
	v_mul_f32_e32 v103, 0x3fb8aa3b, v103
	v_exp_f32_e32 v107, v103
	v_mov_b32_e32 v103, v1
	v_lshl_add_u64 v[102:103], v[102:103], 2, s[48:49]
	global_store_dword v[102:103], v106, off
	v_mul_f32_e32 v102, 0xbfb8aa3b, v107
	v_exp_f32_e32 v103, v102
	v_add_u32_e32 v102, 0x6600, v110
	v_add_u32_e32 v106, v100, v102
	v_mov_b32_e32 v107, v1
	v_lshl_add_u64 v[106:107], v[106:107], 2, s[48:49]
	global_store_dword v[106:107], v103, off
	v_add_f32_e32 v103, v62, v111
	v_max_f32_e64 v106, -v103, 0
	v_mul_f32_e64 v103, |v103|, s0
	v_exp_f32_e32 v103, v103
	v_mov_b32_e32 v159, v1
	v_add_f32_e32 v103, 1.0, v103
	v_cmp_gt_f32_e32 vcc, s31, v103
	s_nop 1
	v_cndmask_b32_e64 v107, 0, 32, vcc
	v_ldexp_f32 v103, v103, v107
	v_log_f32_e32 v103, v103
	s_nop 0
	v_mul_f32_e32 v107, 0x3f317217, v103
	v_fma_f32 v107, v103, s1, -v107
	v_fmac_f32_e32 v107, 0x3377d1cf, v103
	v_fmac_f32_e32 v107, 0x3f317217, v103
	v_cmp_lt_f32_e64 s[42:43], |v103|, s33
	s_nop 1
	v_cndmask_b32_e64 v103, v103, v107, s[42:43]
	v_cndmask_b32_e32 v107, 0, v199, vcc
	v_sub_f32_e32 v103, v103, v107
	v_add_f32_e32 v103, v106, v103
	v_sub_f32_e32 v103, -0.5, v103
	v_mul_f32_e32 v103, 0x3fb8aa3b, v103
	v_exp_f32_e32 v103, v103
	v_mov_b32_e32 v107, v1
	v_mul_f32_e32 v103, 0xbfb8aa3b, v103
	v_exp_f32_e32 v113, v103
	v_add_u32_e32 v103, 0x7000, v110
	v_add_u32_e32 v106, v100, v103
	v_lshl_add_u64 v[106:107], v[106:107], 2, s[48:49]
	global_store_dword v[106:107], v113, off
	v_add_f32_e32 v106, v63, v111
	v_max_f32_e64 v107, -v106, 0
	v_mul_f32_e64 v106, |v106|, s0
	v_exp_f32_e32 v106, v106
	s_nop 0
	v_add_f32_e32 v106, 1.0, v106
	v_cmp_gt_f32_e32 vcc, s31, v106
	s_nop 1
	v_cndmask_b32_e64 v113, 0, 32, vcc
	v_ldexp_f32 v106, v106, v113
	v_log_f32_e32 v106, v106
	s_nop 0
	v_mul_f32_e32 v113, 0x3f317217, v106
	v_fma_f32 v113, v106, s1, -v113
	v_fmac_f32_e32 v113, 0x3377d1cf, v106
	v_fmac_f32_e32 v113, 0x3f317217, v106
	v_cmp_lt_f32_e64 s[42:43], |v106|, s33
	s_nop 1
	v_cndmask_b32_e64 v106, v106, v113, s[42:43]
	v_cndmask_b32_e32 v113, 0, v199, vcc
	v_sub_f32_e32 v106, v106, v113
	v_add_f32_e32 v106, v107, v106
	v_sub_f32_e32 v106, -0.5, v106
	v_mul_f32_e32 v106, 0x3fb8aa3b, v106
	v_exp_f32_e32 v106, v106
	s_nop 0
	v_mul_f32_e32 v106, 0xbfb8aa3b, v106
	v_exp_f32_e32 v107, v106
	v_add_u32_e32 v106, 0x7200, v110
	v_add_u32_e32 v158, v100, v106
	v_lshl_add_u64 v[158:159], v[158:159], 2, s[48:49]
	global_store_dword v[158:159], v107, off
	v_add_f32_e32 v107, v64, v111
	v_max_f32_e64 v113, -v107, 0
	v_mul_f32_e64 v107, |v107|, s0
	v_exp_f32_e32 v107, v107
	v_mov_b32_e32 v159, v1
	v_add_f32_e32 v111, v65, v111
	v_add_f32_e32 v107, 1.0, v107
	v_cmp_gt_f32_e32 vcc, s31, v107
	s_nop 1
	v_cndmask_b32_e64 v158, 0, 32, vcc
	v_ldexp_f32 v107, v107, v158
	v_log_f32_e32 v107, v107
	s_nop 0
	v_mul_f32_e32 v158, 0x3f317217, v107
	v_fma_f32 v158, v107, s1, -v158
	v_fmac_f32_e32 v158, 0x3377d1cf, v107
	v_fmac_f32_e32 v158, 0x3f317217, v107
	v_cmp_lt_f32_e64 s[42:43], |v107|, s33
	s_nop 1
	v_cndmask_b32_e64 v107, v107, v158, s[42:43]
	v_cndmask_b32_e32 v158, 0, v199, vcc
	v_sub_f32_e32 v107, v107, v158
	v_add_f32_e32 v107, v113, v107
	v_sub_f32_e32 v107, -0.5, v107
	v_mul_f32_e32 v107, 0x3fb8aa3b, v107
	v_exp_f32_e32 v107, v107
	s_nop 0
	v_mul_f32_e32 v107, 0xbfb8aa3b, v107
	v_exp_f32_e32 v113, v107
	v_add_u32_e32 v107, 0x7400, v110
	v_add_u32_e32 v158, v100, v107
	v_lshl_add_u64 v[158:159], v[158:159], 2, s[48:49]
	global_store_dword v[158:159], v113, off
	v_max_f32_e64 v113, -v111, 0
	v_mul_f32_e64 v111, |v111|, s0
	v_exp_f32_e32 v111, v111
	v_mov_b32_e32 v159, v1
	v_add_f32_e32 v111, 1.0, v111
	v_cmp_gt_f32_e32 vcc, s31, v111
	s_nop 1
	v_cndmask_b32_e64 v158, 0, 32, vcc
	v_ldexp_f32 v111, v111, v158
	v_log_f32_e32 v111, v111
	s_nop 0
	v_mul_f32_e32 v158, 0x3f317217, v111
	v_fma_f32 v158, v111, s1, -v158
	v_fmac_f32_e32 v158, 0x3377d1cf, v111
	v_fmac_f32_e32 v158, 0x3f317217, v111
	v_cmp_lt_f32_e64 s[42:43], |v111|, s33
	s_nop 1
	v_cndmask_b32_e64 v111, v111, v158, s[42:43]
	v_cndmask_b32_e32 v158, 0, v199, vcc
	v_sub_f32_e32 v111, v111, v158
	v_add_f32_e32 v111, v113, v111
	v_sub_f32_e32 v111, -0.5, v111
	v_mul_f32_e32 v111, 0x3fb8aa3b, v111
	v_exp_f32_e32 v111, v111
	s_nop 0
	v_mul_f32_e32 v111, 0xbfb8aa3b, v111
	v_exp_f32_e32 v113, v111
	v_add_u32_e32 v111, 0x7600, v110
	v_add_u32_e32 v158, v100, v111
	v_lshl_add_u64 v[158:159], v[158:159], 2, s[48:49]
	global_store_dword v[158:159], v113, off
	v_mov_b32_e32 v113, v237
	v_add_f32_e32 v158, v34, v113
	v_max_f32_e64 v159, -v158, 0
	v_mul_f32_e64 v158, |v158|, s0
	v_exp_f32_e32 v158, v158
	v_add_u32_e32 v156, v101, v156
	v_add_f32_e32 v158, 1.0, v158
	v_cmp_gt_f32_e32 vcc, s31, v158
	s_nop 1
	v_cndmask_b32_e64 v160, 0, 32, vcc
	v_ldexp_f32 v158, v158, v160
	v_log_f32_e32 v158, v158
	s_nop 0
	v_mul_f32_e32 v160, 0x3f317217, v158
	v_fma_f32 v160, v158, s1, -v160
	v_fmac_f32_e32 v160, 0x3377d1cf, v158
	v_fmac_f32_e32 v160, 0x3f317217, v158
	v_cmp_lt_f32_e64 s[42:43], |v158|, s33
	s_nop 1
	v_cndmask_b32_e64 v158, v158, v160, s[42:43]
	v_cndmask_b32_e32 v160, 0, v199, vcc
	v_sub_f32_e32 v158, v158, v160
	v_add_f32_e32 v158, v159, v158
	v_sub_f32_e32 v158, -0.5, v158
	v_mul_f32_e32 v158, 0x3fb8aa3b, v158
	v_exp_f32_e32 v158, v158
	v_mov_b32_e32 v159, v1
	v_mul_f32_e32 v158, 0xbfb8aa3b, v158
	v_exp_f32_e32 v160, v158
	v_add_u32_e32 v158, v101, v157
	v_lshl_add_u64 v[158:159], v[158:159], 2, s[48:49]
	v_add_f32_e32 v157, v35, v113
	global_store_dword v[158:159], v160, off
	v_max_f32_e64 v158, -v157, 0
	v_mul_f32_e64 v157, |v157|, s0
	v_exp_f32_e32 v157, v157
	s_nop 0
	v_add_f32_e32 v157, 1.0, v157
	v_cmp_gt_f32_e32 vcc, s31, v157
	s_nop 1
	v_cndmask_b32_e64 v159, 0, 32, vcc
	v_ldexp_f32 v157, v157, v159
	v_log_f32_e32 v157, v157
	s_nop 0
	v_mul_f32_e32 v159, 0x3f317217, v157
	v_fma_f32 v159, v157, s1, -v159
	v_fmac_f32_e32 v159, 0x3377d1cf, v157
	v_fmac_f32_e32 v159, 0x3f317217, v157
	v_cmp_lt_f32_e64 s[42:43], |v157|, s33
	s_nop 1
	v_cndmask_b32_e64 v157, v157, v159, s[42:43]
	v_cndmask_b32_e32 v159, 0, v199, vcc
	v_sub_f32_e32 v157, v157, v159
	v_add_f32_e32 v157, v158, v157
	v_sub_f32_e32 v157, -0.5, v157
	v_mul_f32_e32 v157, 0x3fb8aa3b, v157
	v_exp_f32_e32 v157, v157
	s_nop 0
	v_mul_f32_e32 v157, 0xbfb8aa3b, v157
	v_exp_f32_e32 v158, v157
	v_mov_b32_e32 v157, v1
	v_lshl_add_u64 v[156:157], v[156:157], 2, s[48:49]
	global_store_dword v[156:157], v158, off
	v_add_f32_e32 v156, v36, v113
	v_max_f32_e64 v157, -v156, 0
	v_mul_f32_e64 v156, |v156|, s0
	v_exp_f32_e32 v156, v156
	s_nop 0
	v_add_f32_e32 v156, 1.0, v156
	v_cmp_gt_f32_e32 vcc, s31, v156
	s_nop 1
	v_cndmask_b32_e64 v158, 0, 32, vcc
	v_ldexp_f32 v156, v156, v158
	v_log_f32_e32 v156, v156
	s_nop 0
	v_mul_f32_e32 v158, 0x3f317217, v156
	v_fma_f32 v158, v156, s1, -v158
	v_fmac_f32_e32 v158, 0x3377d1cf, v156
	v_fmac_f32_e32 v158, 0x3f317217, v156
	v_cmp_lt_f32_e64 s[42:43], |v156|, s33
	s_nop 1
	v_cndmask_b32_e64 v156, v156, v158, s[42:43]
	v_cndmask_b32_e32 v158, 0, v199, vcc
	v_sub_f32_e32 v156, v156, v158
	v_add_f32_e32 v156, v157, v156
	v_sub_f32_e32 v156, -0.5, v156
	v_mul_f32_e32 v156, 0x3fb8aa3b, v156
	v_exp_f32_e32 v156, v156
	v_mov_b32_e32 v157, v1
	v_mul_f32_e32 v156, 0xbfb8aa3b, v156
	v_exp_f32_e32 v158, v156
	v_add_u32_e32 v156, v101, v155
	v_lshl_add_u64 v[156:157], v[156:157], 2, s[48:49]
	v_add_f32_e32 v155, v37, v113
	global_store_dword v[156:157], v158, off
	v_max_f32_e64 v156, -v155, 0
	v_mul_f32_e64 v155, |v155|, s0
	v_exp_f32_e32 v155, v155
	s_nop 0
	v_add_f32_e32 v155, 1.0, v155
	v_cmp_gt_f32_e32 vcc, s31, v155
	s_nop 1
	v_cndmask_b32_e64 v157, 0, 32, vcc
	v_ldexp_f32 v155, v155, v157
	v_log_f32_e32 v155, v155
	s_nop 0
	v_mul_f32_e32 v157, 0x3f317217, v155
	v_fma_f32 v157, v155, s1, -v157
	v_fmac_f32_e32 v157, 0x3377d1cf, v155
	v_fmac_f32_e32 v157, 0x3f317217, v155
	v_cmp_lt_f32_e64 s[42:43], |v155|, s33
	s_nop 1
	v_cndmask_b32_e64 v155, v155, v157, s[42:43]
	v_cndmask_b32_e32 v157, 0, v199, vcc
	v_sub_f32_e32 v155, v155, v157
	v_add_f32_e32 v155, v156, v155
	v_sub_f32_e32 v155, -0.5, v155
	v_mul_f32_e32 v155, 0x3fb8aa3b, v155
	v_exp_f32_e32 v155, v155
	v_add_u32_e32 v156, v101, v153
	v_mov_b32_e32 v157, v1
	v_lshl_add_u64 v[156:157], v[156:157], 2, s[48:49]
	v_mul_f32_e32 v155, 0xbfb8aa3b, v155
	v_exp_f32_e32 v155, v155
	global_store_dword v[156:157], v155, off
	v_add_f32_e32 v153, v38, v113
	v_max_f32_e64 v155, -v153, 0
	v_mul_f32_e64 v153, |v153|, s0
	v_exp_f32_e32 v153, v153
	v_add_u32_e32 v154, v101, v154
	v_add_u32_e32 v152, v101, v152
	v_add_f32_e32 v153, 1.0, v153
	v_cmp_gt_f32_e32 vcc, s31, v153
	s_nop 1
	v_cndmask_b32_e64 v156, 0, 32, vcc
	v_ldexp_f32 v153, v153, v156
	v_log_f32_e32 v153, v153
	s_nop 0
	v_mul_f32_e32 v156, 0x3f317217, v153
	v_fma_f32 v156, v153, s1, -v156
	v_fmac_f32_e32 v156, 0x3377d1cf, v153
	v_fmac_f32_e32 v156, 0x3f317217, v153
	v_cmp_lt_f32_e64 s[42:43], |v153|, s33
	s_nop 1
	v_cndmask_b32_e64 v153, v153, v156, s[42:43]
	v_cndmask_b32_e32 v156, 0, v199, vcc
	v_sub_f32_e32 v153, v153, v156
	v_add_f32_e32 v153, v155, v153
	v_sub_f32_e32 v153, -0.5, v153
	v_mul_f32_e32 v153, 0x3fb8aa3b, v153
	v_exp_f32_e32 v153, v153
	v_mov_b32_e32 v155, v1
	v_lshl_add_u64 v[154:155], v[154:155], 2, s[48:49]
	v_mul_f32_e32 v153, 0xbfb8aa3b, v153
	v_exp_f32_e32 v153, v153
	global_store_dword v[154:155], v153, off
	v_add_f32_e32 v153, v39, v113
	v_max_f32_e64 v154, -v153, 0
	v_mul_f32_e64 v153, |v153|, s0
	v_exp_f32_e32 v153, v153
	s_nop 0
	v_add_f32_e32 v153, 1.0, v153
	v_cmp_gt_f32_e32 vcc, s31, v153
	s_nop 1
	v_cndmask_b32_e64 v155, 0, 32, vcc
	v_ldexp_f32 v153, v153, v155
	v_log_f32_e32 v153, v153
	s_nop 0
	v_mul_f32_e32 v155, 0x3f317217, v153
	v_fma_f32 v155, v153, s1, -v155
	v_fmac_f32_e32 v155, 0x3377d1cf, v153
	v_fmac_f32_e32 v155, 0x3f317217, v153
	v_cmp_lt_f32_e64 s[42:43], |v153|, s33
	s_nop 1
	v_cndmask_b32_e64 v153, v153, v155, s[42:43]
	v_cndmask_b32_e32 v155, 0, v199, vcc
	v_sub_f32_e32 v153, v153, v155
	v_add_f32_e32 v153, v154, v153
	v_sub_f32_e32 v153, -0.5, v153
	v_mul_f32_e32 v153, 0x3fb8aa3b, v153
	v_exp_f32_e32 v153, v153
	s_nop 0
	v_mul_f32_e32 v153, 0xbfb8aa3b, v153
	v_exp_f32_e32 v154, v153
	v_mov_b32_e32 v153, v1
	v_lshl_add_u64 v[152:153], v[152:153], 2, s[48:49]
	global_store_dword v[152:153], v154, off
	v_add_f32_e32 v152, v40, v113
	v_max_f32_e64 v153, -v152, 0
	v_mul_f32_e64 v152, |v152|, s0
	v_exp_f32_e32 v152, v152
	s_nop 0
	v_add_f32_e32 v152, 1.0, v152
	v_cmp_gt_f32_e32 vcc, s31, v152
	s_nop 1
	v_cndmask_b32_e64 v154, 0, 32, vcc
	v_ldexp_f32 v152, v152, v154
	v_log_f32_e32 v152, v152
	s_nop 0
	v_mul_f32_e32 v154, 0x3f317217, v152
	v_fma_f32 v154, v152, s1, -v154
	v_fmac_f32_e32 v154, 0x3377d1cf, v152
	v_fmac_f32_e32 v154, 0x3f317217, v152
	v_cmp_lt_f32_e64 s[42:43], |v152|, s33
	s_nop 1
	v_cndmask_b32_e64 v152, v152, v154, s[42:43]
	v_cndmask_b32_e32 v154, 0, v199, vcc
	v_sub_f32_e32 v152, v152, v154
	v_add_f32_e32 v152, v153, v152
	v_sub_f32_e32 v152, -0.5, v152
	v_mul_f32_e32 v152, 0x3fb8aa3b, v152
	v_exp_f32_e32 v152, v152
	v_mov_b32_e32 v153, v1
	v_mul_f32_e32 v152, 0xbfb8aa3b, v152
	v_exp_f32_e32 v154, v152
	v_add_u32_e32 v152, v101, v151
	v_lshl_add_u64 v[152:153], v[152:153], 2, s[48:49]
	v_add_f32_e32 v151, v41, v113
	global_store_dword v[152:153], v154, off
	v_max_f32_e64 v152, -v151, 0
	v_mul_f32_e64 v151, |v151|, s0
	v_exp_f32_e32 v151, v151
	s_nop 0
	v_add_f32_e32 v151, 1.0, v151
	v_cmp_gt_f32_e32 vcc, s31, v151
	s_nop 1
	v_cndmask_b32_e64 v153, 0, 32, vcc
	v_ldexp_f32 v151, v151, v153
	v_log_f32_e32 v151, v151
	s_nop 0
	v_mul_f32_e32 v153, 0x3f317217, v151
	v_fma_f32 v153, v151, s1, -v153
	v_fmac_f32_e32 v153, 0x3377d1cf, v151
	v_fmac_f32_e32 v153, 0x3f317217, v151
	v_cmp_lt_f32_e64 s[42:43], |v151|, s33
	s_nop 1
	v_cndmask_b32_e64 v151, v151, v153, s[42:43]
	v_cndmask_b32_e32 v153, 0, v199, vcc
	v_sub_f32_e32 v151, v151, v153
	v_add_f32_e32 v151, v152, v151
	v_sub_f32_e32 v151, -0.5, v151
	v_mul_f32_e32 v151, 0x3fb8aa3b, v151
	v_exp_f32_e32 v151, v151
	v_add_u32_e32 v152, v101, v149
	v_mov_b32_e32 v153, v1
	v_lshl_add_u64 v[152:153], v[152:153], 2, s[48:49]
	v_mul_f32_e32 v151, 0xbfb8aa3b, v151
	v_exp_f32_e32 v151, v151
	global_store_dword v[152:153], v151, off
	v_add_f32_e32 v149, v42, v113
	v_max_f32_e64 v151, -v149, 0
	v_mul_f32_e64 v149, |v149|, s0
	v_exp_f32_e32 v149, v149
	v_add_u32_e32 v150, v101, v150
	v_add_u32_e32 v148, v101, v148
	v_add_f32_e32 v149, 1.0, v149
	v_cmp_gt_f32_e32 vcc, s31, v149
	s_nop 1
	v_cndmask_b32_e64 v152, 0, 32, vcc
	v_ldexp_f32 v149, v149, v152
	v_log_f32_e32 v149, v149
	s_nop 0
	v_mul_f32_e32 v152, 0x3f317217, v149
	v_fma_f32 v152, v149, s1, -v152
	v_fmac_f32_e32 v152, 0x3377d1cf, v149
	v_fmac_f32_e32 v152, 0x3f317217, v149
	v_cmp_lt_f32_e64 s[42:43], |v149|, s33
	s_nop 1
	v_cndmask_b32_e64 v149, v149, v152, s[42:43]
	v_cndmask_b32_e32 v152, 0, v199, vcc
	v_sub_f32_e32 v149, v149, v152
	v_add_f32_e32 v149, v151, v149
	v_sub_f32_e32 v149, -0.5, v149
	v_mul_f32_e32 v149, 0x3fb8aa3b, v149
	v_exp_f32_e32 v149, v149
	v_mov_b32_e32 v151, v1
	v_lshl_add_u64 v[150:151], v[150:151], 2, s[48:49]
	v_mul_f32_e32 v149, 0xbfb8aa3b, v149
	v_exp_f32_e32 v149, v149
	global_store_dword v[150:151], v149, off
	v_add_f32_e32 v149, v43, v113
	v_max_f32_e64 v150, -v149, 0
	v_mul_f32_e64 v149, |v149|, s0
	v_exp_f32_e32 v149, v149
	s_nop 0
	v_add_f32_e32 v149, 1.0, v149
	v_cmp_gt_f32_e32 vcc, s31, v149
	s_nop 1
	v_cndmask_b32_e64 v151, 0, 32, vcc
	v_ldexp_f32 v149, v149, v151
	v_log_f32_e32 v149, v149
	s_nop 0
	v_mul_f32_e32 v151, 0x3f317217, v149
	v_fma_f32 v151, v149, s1, -v151
	v_fmac_f32_e32 v151, 0x3377d1cf, v149
	v_fmac_f32_e32 v151, 0x3f317217, v149
	v_cmp_lt_f32_e64 s[42:43], |v149|, s33
	s_nop 1
	v_cndmask_b32_e64 v149, v149, v151, s[42:43]
	v_cndmask_b32_e32 v151, 0, v199, vcc
	v_sub_f32_e32 v149, v149, v151
	v_add_f32_e32 v149, v150, v149
	v_sub_f32_e32 v149, -0.5, v149
	v_mul_f32_e32 v149, 0x3fb8aa3b, v149
	v_exp_f32_e32 v149, v149
	s_nop 0
	v_mul_f32_e32 v149, 0xbfb8aa3b, v149
	v_exp_f32_e32 v150, v149
	v_mov_b32_e32 v149, v1
	v_lshl_add_u64 v[148:149], v[148:149], 2, s[48:49]
	global_store_dword v[148:149], v150, off
	v_add_f32_e32 v148, v44, v113
	v_max_f32_e64 v149, -v148, 0
	v_mul_f32_e64 v148, |v148|, s0
	v_exp_f32_e32 v148, v148
	s_nop 0
	v_add_f32_e32 v148, 1.0, v148
	v_cmp_gt_f32_e32 vcc, s31, v148
	s_nop 1
	v_cndmask_b32_e64 v150, 0, 32, vcc
	v_ldexp_f32 v148, v148, v150
	v_log_f32_e32 v148, v148
	s_nop 0
	v_mul_f32_e32 v150, 0x3f317217, v148
	v_fma_f32 v150, v148, s1, -v150
	v_fmac_f32_e32 v150, 0x3377d1cf, v148
	v_fmac_f32_e32 v150, 0x3f317217, v148
	v_cmp_lt_f32_e64 s[42:43], |v148|, s33
	s_nop 1
	v_cndmask_b32_e64 v148, v148, v150, s[42:43]
	v_cndmask_b32_e32 v150, 0, v199, vcc
	v_sub_f32_e32 v148, v148, v150
	v_add_f32_e32 v148, v149, v148
	v_sub_f32_e32 v148, -0.5, v148
	v_mul_f32_e32 v148, 0x3fb8aa3b, v148
	v_exp_f32_e32 v148, v148
	v_mov_b32_e32 v149, v1
	v_mul_f32_e32 v148, 0xbfb8aa3b, v148
	v_exp_f32_e32 v150, v148
	v_add_u32_e32 v148, v101, v112
	v_lshl_add_u64 v[148:149], v[148:149], 2, s[48:49]
	v_add_f32_e32 v112, v45, v113
	global_store_dword v[148:149], v150, off
	v_max_f32_e64 v148, -v112, 0
	v_mul_f32_e64 v112, |v112|, s0
	v_exp_f32_e32 v112, v112
	s_nop 0
	v_add_f32_e32 v112, 1.0, v112
	v_cmp_gt_f32_e32 vcc, s31, v112
	s_nop 1
	v_cndmask_b32_e64 v149, 0, 32, vcc
	v_ldexp_f32 v112, v112, v149
	v_log_f32_e32 v112, v112
	s_nop 0
	v_mul_f32_e32 v149, 0x3f317217, v112
	v_fma_f32 v149, v112, s1, -v149
	v_fmac_f32_e32 v149, 0x3377d1cf, v112
	v_fmac_f32_e32 v149, 0x3f317217, v112
	v_cmp_lt_f32_e64 s[42:43], |v112|, s33
	s_nop 1
	v_cndmask_b32_e64 v112, v112, v149, s[42:43]
	v_cndmask_b32_e32 v149, 0, v199, vcc
	v_sub_f32_e32 v112, v112, v149
	v_add_f32_e32 v112, v148, v112
	v_sub_f32_e32 v112, -0.5, v112
	v_mul_f32_e32 v112, 0x3fb8aa3b, v112
	v_exp_f32_e32 v112, v112
	v_add_u32_e32 v148, v101, v102
	v_mov_b32_e32 v149, v1
	v_lshl_add_u64 v[148:149], v[148:149], 2, s[48:49]
	v_mul_f32_e32 v112, 0xbfb8aa3b, v112
	v_exp_f32_e32 v112, v112
	global_store_dword v[148:149], v112, off
	v_add_f32_e32 v102, v46, v113
	v_max_f32_e64 v112, -v102, 0
	v_mul_f32_e64 v102, |v102|, s0
	v_exp_f32_e32 v102, v102
	s_nop 0
	v_add_f32_e32 v102, 1.0, v102
	v_cmp_gt_f32_e32 vcc, s31, v102
	s_nop 1
	v_cndmask_b32_e64 v148, 0, 32, vcc
	v_ldexp_f32 v102, v102, v148
	v_log_f32_e32 v102, v102
	s_nop 0
	v_mul_f32_e32 v148, 0x3f317217, v102
	v_fma_f32 v148, v102, s1, -v148
	v_fmac_f32_e32 v148, 0x3377d1cf, v102
	v_fmac_f32_e32 v148, 0x3f317217, v102
	v_cmp_lt_f32_e64 s[42:43], |v102|, s33
	s_nop 1
	v_cndmask_b32_e64 v102, v102, v148, s[42:43]
	v_cndmask_b32_e32 v148, 0, v199, vcc
	v_sub_f32_e32 v102, v102, v148
	v_add_f32_e32 v102, v112, v102
	v_sub_f32_e32 v102, -0.5, v102
	v_mul_f32_e32 v102, 0x3fb8aa3b, v102
	v_exp_f32_e32 v102, v102
	s_nop 0
	v_mul_f32_e32 v102, 0xbfb8aa3b, v102
	v_exp_f32_e32 v112, v102
	v_add_u32_e32 v102, v101, v103
	v_mov_b32_e32 v103, v1
	v_lshl_add_u64 v[102:103], v[102:103], 2, s[48:49]
	global_store_dword v[102:103], v112, off
	v_add_f32_e32 v102, v47, v113
	v_max_f32_e64 v103, -v102, 0
	v_mul_f32_e64 v102, |v102|, s0
	v_exp_f32_e32 v102, v102
	s_nop 0
	v_add_f32_e32 v102, 1.0, v102
	v_cmp_gt_f32_e32 vcc, s31, v102
	s_nop 1
	v_cndmask_b32_e64 v112, 0, 32, vcc
	v_ldexp_f32 v102, v102, v112
	v_log_f32_e32 v102, v102
	s_nop 0
	v_mul_f32_e32 v112, 0x3f317217, v102
	v_fma_f32 v112, v102, s1, -v112
	v_fmac_f32_e32 v112, 0x3377d1cf, v102
	v_fmac_f32_e32 v112, 0x3f317217, v102
	v_cmp_lt_f32_e64 s[42:43], |v102|, s33
	s_nop 1
	v_cndmask_b32_e64 v102, v102, v112, s[42:43]
	v_cndmask_b32_e32 v112, 0, v199, vcc
	v_sub_f32_e32 v102, v102, v112
	v_add_f32_e32 v102, v103, v102
	v_sub_f32_e32 v102, -0.5, v102
	v_mul_f32_e32 v102, 0x3fb8aa3b, v102
	v_exp_f32_e32 v102, v102
	v_mov_b32_e32 v103, v1
	v_mul_f32_e32 v102, 0xbfb8aa3b, v102
	v_exp_f32_e32 v112, v102
	v_add_u32_e32 v102, v101, v106
	v_lshl_add_u64 v[102:103], v[102:103], 2, s[48:49]
	global_store_dword v[102:103], v112, off
	v_add_f32_e32 v102, v48, v113
	v_max_f32_e64 v103, -v102, 0
	v_mul_f32_e64 v102, |v102|, s0
	v_exp_f32_e32 v102, v102
	s_nop 0
	v_add_f32_e32 v102, 1.0, v102
	v_cmp_gt_f32_e32 vcc, s31, v102
	s_nop 1
	v_cndmask_b32_e64 v106, 0, 32, vcc
	v_ldexp_f32 v102, v102, v106
	v_log_f32_e32 v102, v102
	s_nop 0
	v_mul_f32_e32 v106, 0x3f317217, v102
	v_fma_f32 v106, v102, s1, -v106
	v_fmac_f32_e32 v106, 0x3377d1cf, v102
	v_fmac_f32_e32 v106, 0x3f317217, v102
	v_cmp_lt_f32_e64 s[42:43], |v102|, s33
	s_nop 1
	v_cndmask_b32_e64 v102, v102, v106, s[42:43]
	v_cndmask_b32_e32 v106, 0, v199, vcc
	v_sub_f32_e32 v102, v102, v106
	v_add_f32_e32 v102, v103, v102
	v_sub_f32_e32 v102, -0.5, v102
	v_mul_f32_e32 v102, 0x3fb8aa3b, v102
	v_exp_f32_e32 v102, v102
	v_mov_b32_e32 v103, v1
	v_mul_f32_e32 v102, 0xbfb8aa3b, v102
	v_exp_f32_e32 v106, v102
	v_add_u32_e32 v102, v101, v107
	v_lshl_add_u64 v[102:103], v[102:103], 2, s[48:49]
	global_store_dword v[102:103], v106, off
	v_add_f32_e32 v102, v49, v113
	v_max_f32_e64 v103, -v102, 0
	v_mul_f32_e64 v102, |v102|, s0
	v_exp_f32_e32 v102, v102
	s_nop 0
	v_add_f32_e32 v102, 1.0, v102
	v_cmp_gt_f32_e32 vcc, s31, v102
	s_nop 1
	v_cndmask_b32_e64 v106, 0, 32, vcc
	v_ldexp_f32 v102, v102, v106
	v_log_f32_e32 v102, v102
	s_nop 0
	v_mul_f32_e32 v106, 0x3f317217, v102
	v_fma_f32 v106, v102, s1, -v106
	v_fmac_f32_e32 v106, 0x3377d1cf, v102
	v_fmac_f32_e32 v106, 0x3f317217, v102
	v_cmp_lt_f32_e64 s[42:43], |v102|, s33
	s_nop 1
	v_cndmask_b32_e64 v102, v102, v106, s[42:43]
	v_cndmask_b32_e32 v106, 0, v199, vcc
	v_sub_f32_e32 v102, v102, v106
	v_add_f32_e32 v102, v103, v102
	v_sub_f32_e32 v102, -0.5, v102
	v_mul_f32_e32 v102, 0x3fb8aa3b, v102
	v_exp_f32_e32 v102, v102
	v_mov_b32_e32 v103, v1
	v_mul_f32_e32 v102, 0xbfb8aa3b, v102
	v_exp_f32_e32 v106, v102
	v_add_u32_e32 v102, v101, v111
	v_lshl_add_u64 v[102:103], v[102:103], 2, s[48:49]
	global_store_dword v[102:103], v106, off
	v_mov_b32_e32 v156, v236
	v_add_f32_e32 v102, v18, v156
	v_mul_f32_e64 v103, |v102|, s0
	v_exp_f32_e32 v103, v103
	v_max_f32_e64 v102, -v102, 0
	v_add_f32_e32 v106, v19, v156
	v_add_u32_e32 v155, 0x8000, v110
	v_add_f32_e32 v103, 1.0, v103
	v_cmp_gt_f32_e32 vcc, s31, v103
	v_add_u32_e32 v154, 0x8200, v110
	v_add_u32_e32 v153, 0x8400, v110
	v_cndmask_b32_e64 v107, 0, 32, vcc
	v_ldexp_f32 v103, v103, v107
	v_log_f32_e32 v103, v103
	v_cndmask_b32_e32 v111, 0, v199, vcc
	v_mul_f32_e64 v107, |v106|, s0
	v_max_f32_e64 v106, -v106, 0
	v_mul_f32_e32 v112, 0x3f317217, v103
	v_fma_f32 v112, v103, s1, -v112
	v_fmac_f32_e32 v112, 0x3377d1cf, v103
	v_fmac_f32_e32 v112, 0x3f317217, v103
	v_cmp_lt_f32_e64 vcc, |v103|, s33
	v_add_u32_e32 v151, 0x8600, v110
	s_nop 0
	v_cndmask_b32_e32 v103, v103, v112, vcc
	v_sub_f32_e32 v103, v103, v111
	v_add_f32_e32 v102, v102, v103
	v_sub_f32_e32 v102, -0.5, v102
	v_mul_f32_e32 v102, 0x3fb8aa3b, v102
	v_exp_f32_e32 v103, v107
	v_exp_f32_e32 v102, v102
	v_add_f32_e32 v103, 1.0, v103
	v_mul_f32_e32 v102, 0xbfb8aa3b, v102
	v_cmp_gt_f32_e32 vcc, s31, v103
	v_exp_f32_e32 v107, v102
	s_nop 0
	v_cndmask_b32_e64 v102, 0, 32, vcc
	v_ldexp_f32 v102, v103, v102
	v_log_f32_e32 v103, v102
	v_add_u32_e32 v102, v100, v155
	v_mul_f32_e32 v111, 0x3f317217, v103
	v_fma_f32 v111, v103, s1, -v111
	v_fmac_f32_e32 v111, 0x3377d1cf, v103
	v_fmac_f32_e32 v111, 0x3f317217, v103
	v_cmp_lt_f32_e64 s[42:43], |v103|, s33
	s_nop 1
	v_cndmask_b32_e64 v103, v103, v111, s[42:43]
	v_cndmask_b32_e32 v111, 0, v199, vcc
	v_sub_f32_e32 v103, v103, v111
	v_add_f32_e32 v103, v106, v103
	v_sub_f32_e32 v103, -0.5, v103
	v_mul_f32_e32 v103, 0x3fb8aa3b, v103
	v_exp_f32_e32 v106, v103
	v_mov_b32_e32 v103, v1
	v_lshl_add_u64 v[102:103], v[102:103], 2, s[48:49]
	global_store_dword v[102:103], v107, off
	v_mul_f32_e32 v102, 0xbfb8aa3b, v106
	v_add_f32_e32 v106, v20, v156
	v_mul_f32_e64 v103, |v106|, s0
	v_exp_f32_e32 v103, v103
	v_max_f32_e64 v106, -v106, 0
	v_exp_f32_e32 v107, v102
	v_add_u32_e32 v102, v100, v154
	v_add_f32_e32 v103, 1.0, v103
	v_cmp_gt_f32_e32 vcc, s31, v103
	s_nop 1
	v_cndmask_b32_e64 v111, 0, 32, vcc
	v_ldexp_f32 v103, v103, v111
	v_log_f32_e32 v111, v103
	v_mov_b32_e32 v103, v1
	v_lshl_add_u64 v[102:103], v[102:103], 2, s[48:49]
	global_store_dword v[102:103], v107, off
	v_mul_f32_e32 v112, 0x3f317217, v111
	v_fma_f32 v112, v111, s1, -v112
	v_fmac_f32_e32 v112, 0x3377d1cf, v111
	v_fmac_f32_e32 v112, 0x3f317217, v111
	v_cmp_lt_f32_e64 s[42:43], |v111|, s33
	s_nop 1
	v_cndmask_b32_e64 v111, v111, v112, s[42:43]
	v_cndmask_b32_e32 v112, 0, v199, vcc
	v_sub_f32_e32 v111, v111, v112
	v_add_f32_e32 v106, v106, v111
	v_sub_f32_e32 v106, -0.5, v106
	v_mul_f32_e32 v106, 0x3fb8aa3b, v106
	v_add_f32_e32 v111, v21, v156
	v_exp_f32_e32 v106, v106
	v_mul_f32_e64 v112, |v111|, s0
	v_exp_f32_e32 v112, v112
	v_max_f32_e64 v107, -v111, 0
	v_mul_f32_e32 v102, 0xbfb8aa3b, v106
	v_exp_f32_e32 v106, v102
	v_add_f32_e32 v102, 1.0, v112
	v_cmp_gt_f32_e32 vcc, s31, v102
	s_nop 1
	v_cndmask_b32_e64 v103, 0, 32, vcc
	v_ldexp_f32 v102, v102, v103
	v_log_f32_e32 v103, v102
	v_add_u32_e32 v102, v100, v153
	v_mul_f32_e32 v111, 0x3f317217, v103
	v_fma_f32 v111, v103, s1, -v111
	v_fmac_f32_e32 v111, 0x3377d1cf, v103
	v_fmac_f32_e32 v111, 0x3f317217, v103
	v_cmp_lt_f32_e64 s[42:43], |v103|, s33
	s_nop 1
	v_cndmask_b32_e64 v103, v103, v111, s[42:43]
	v_cndmask_b32_e32 v111, 0, v199, vcc
	v_sub_f32_e32 v103, v103, v111
	v_add_f32_e32 v103, v107, v103
	v_sub_f32_e32 v103, -0.5, v103
	v_mul_f32_e32 v103, 0x3fb8aa3b, v103
	v_exp_f32_e32 v107, v103
	v_mov_b32_e32 v103, v1
	v_lshl_add_u64 v[102:103], v[102:103], 2, s[48:49]
	global_store_dword v[102:103], v106, off
	v_mul_f32_e32 v102, 0xbfb8aa3b, v107
	v_exp_f32_e32 v106, v102
	v_add_u32_e32 v102, v100, v151
	v_mov_b32_e32 v103, v1
	v_lshl_add_u64 v[102:103], v[102:103], 2, s[48:49]
	global_store_dword v[102:103], v106, off
	v_add_f32_e32 v102, v22, v156
	v_mul_f32_e64 v103, |v102|, s0
	v_exp_f32_e32 v103, v103
	v_max_f32_e64 v102, -v102, 0
	v_add_f32_e32 v106, v23, v156
	v_add_u32_e32 v152, 0x9000, v110
	v_add_f32_e32 v103, 1.0, v103
	v_cmp_gt_f32_e32 vcc, s31, v103
	v_add_u32_e32 v150, 0x9200, v110
	v_add_u32_e32 v149, 0x9400, v110
	v_cndmask_b32_e64 v107, 0, 32, vcc
	v_ldexp_f32 v103, v103, v107
	v_log_f32_e32 v103, v103
	v_cndmask_b32_e32 v111, 0, v199, vcc
	v_mul_f32_e64 v107, |v106|, s0
	v_max_f32_e64 v106, -v106, 0
	v_mul_f32_e32 v112, 0x3f317217, v103
	v_fma_f32 v112, v103, s1, -v112
	v_fmac_f32_e32 v112, 0x3377d1cf, v103
	v_fmac_f32_e32 v112, 0x3f317217, v103
	v_cmp_lt_f32_e64 vcc, |v103|, s33
	v_add_u32_e32 v113, 0x9600, v110
	s_nop 0
	v_cndmask_b32_e32 v103, v103, v112, vcc
	v_sub_f32_e32 v103, v103, v111
	v_add_f32_e32 v102, v102, v103
	v_sub_f32_e32 v102, -0.5, v102
	v_mul_f32_e32 v102, 0x3fb8aa3b, v102
	v_exp_f32_e32 v103, v107
	v_exp_f32_e32 v102, v102
	v_add_f32_e32 v103, 1.0, v103
	v_mul_f32_e32 v102, 0xbfb8aa3b, v102
	v_cmp_gt_f32_e32 vcc, s31, v103
	v_exp_f32_e32 v107, v102
	s_nop 0
	v_cndmask_b32_e64 v102, 0, 32, vcc
	v_ldexp_f32 v102, v103, v102
	v_log_f32_e32 v103, v102
	v_add_u32_e32 v102, v100, v152
	v_mul_f32_e32 v111, 0x3f317217, v103
	v_fma_f32 v111, v103, s1, -v111
	v_fmac_f32_e32 v111, 0x3377d1cf, v103
	v_fmac_f32_e32 v111, 0x3f317217, v103
	v_cmp_lt_f32_e64 s[42:43], |v103|, s33
	s_nop 1
	v_cndmask_b32_e64 v103, v103, v111, s[42:43]
	v_cndmask_b32_e32 v111, 0, v199, vcc
	v_sub_f32_e32 v103, v103, v111
	v_add_f32_e32 v103, v106, v103
	v_sub_f32_e32 v103, -0.5, v103
	v_mul_f32_e32 v103, 0x3fb8aa3b, v103
	v_exp_f32_e32 v106, v103
	v_mov_b32_e32 v103, v1
	v_lshl_add_u64 v[102:103], v[102:103], 2, s[48:49]
	global_store_dword v[102:103], v107, off
	v_mul_f32_e32 v102, 0xbfb8aa3b, v106
	v_add_f32_e32 v106, v24, v156
	v_mul_f32_e64 v103, |v106|, s0
	v_exp_f32_e32 v103, v103
	v_max_f32_e64 v106, -v106, 0
	v_exp_f32_e32 v107, v102
	v_add_u32_e32 v102, v100, v150
	v_add_f32_e32 v103, 1.0, v103
	v_cmp_gt_f32_e32 vcc, s31, v103
	s_nop 1
	v_cndmask_b32_e64 v111, 0, 32, vcc
	v_ldexp_f32 v103, v103, v111
	v_log_f32_e32 v111, v103
	v_mov_b32_e32 v103, v1
	v_lshl_add_u64 v[102:103], v[102:103], 2, s[48:49]
	global_store_dword v[102:103], v107, off
	v_mul_f32_e32 v112, 0x3f317217, v111
	v_fma_f32 v112, v111, s1, -v112
	v_fmac_f32_e32 v112, 0x3377d1cf, v111
	v_fmac_f32_e32 v112, 0x3f317217, v111
	v_cmp_lt_f32_e64 s[42:43], |v111|, s33
	s_nop 1
	v_cndmask_b32_e64 v111, v111, v112, s[42:43]
	v_cndmask_b32_e32 v112, 0, v199, vcc
	v_sub_f32_e32 v111, v111, v112
	v_add_f32_e32 v106, v106, v111
	v_sub_f32_e32 v106, -0.5, v106
	v_mul_f32_e32 v106, 0x3fb8aa3b, v106
	v_add_f32_e32 v111, v25, v156
	v_exp_f32_e32 v106, v106
	v_mul_f32_e64 v112, |v111|, s0
	v_exp_f32_e32 v112, v112
	v_max_f32_e64 v107, -v111, 0
	v_mul_f32_e32 v102, 0xbfb8aa3b, v106
	v_exp_f32_e32 v106, v102
	v_add_f32_e32 v102, 1.0, v112
	v_cmp_gt_f32_e32 vcc, s31, v102
	s_nop 1
	v_cndmask_b32_e64 v103, 0, 32, vcc
	v_ldexp_f32 v102, v102, v103
	v_log_f32_e32 v103, v102
	v_add_u32_e32 v102, v100, v149
	v_mul_f32_e32 v111, 0x3f317217, v103
	v_fma_f32 v111, v103, s1, -v111
	v_fmac_f32_e32 v111, 0x3377d1cf, v103
	v_fmac_f32_e32 v111, 0x3f317217, v103
	v_cmp_lt_f32_e64 s[42:43], |v103|, s33
	s_nop 1
	v_cndmask_b32_e64 v103, v103, v111, s[42:43]
	v_cndmask_b32_e32 v111, 0, v199, vcc
	v_sub_f32_e32 v103, v103, v111
	v_add_f32_e32 v103, v107, v103
	v_sub_f32_e32 v103, -0.5, v103
	v_mul_f32_e32 v103, 0x3fb8aa3b, v103
	v_exp_f32_e32 v107, v103
	v_mov_b32_e32 v103, v1
	v_lshl_add_u64 v[102:103], v[102:103], 2, s[48:49]
	global_store_dword v[102:103], v106, off
	v_mul_f32_e32 v102, 0xbfb8aa3b, v107
	v_exp_f32_e32 v106, v102
	v_add_u32_e32 v102, v100, v113
	v_mov_b32_e32 v103, v1
	v_lshl_add_u64 v[102:103], v[102:103], 2, s[48:49]
	global_store_dword v[102:103], v106, off
	v_add_f32_e32 v102, v26, v156
	v_mul_f32_e64 v103, |v102|, s0
	v_exp_f32_e32 v103, v103
	v_max_f32_e64 v102, -v102, 0
	v_add_f32_e32 v106, v27, v156
	v_add_u32_e32 v148, 0xa000, v110
	v_add_f32_e32 v103, 1.0, v103
	v_cmp_gt_f32_e32 vcc, s31, v103
	s_nop 1
	v_cndmask_b32_e64 v107, 0, 32, vcc
	v_ldexp_f32 v103, v103, v107
	v_log_f32_e32 v103, v103
	v_cndmask_b32_e32 v111, 0, v199, vcc
	v_mul_f32_e64 v107, |v106|, s0
	v_max_f32_e64 v106, -v106, 0
	v_mul_f32_e32 v112, 0x3f317217, v103
	v_fma_f32 v112, v103, s1, -v112
	v_fmac_f32_e32 v112, 0x3377d1cf, v103
	v_fmac_f32_e32 v112, 0x3f317217, v103
	v_cmp_lt_f32_e64 vcc, |v103|, s33
	s_nop 1
	v_cndmask_b32_e32 v103, v103, v112, vcc
	v_sub_f32_e32 v103, v103, v111
	v_add_f32_e32 v102, v102, v103
	v_sub_f32_e32 v102, -0.5, v102
	v_mul_f32_e32 v102, 0x3fb8aa3b, v102
	v_exp_f32_e32 v103, v107
	v_exp_f32_e32 v102, v102
	v_add_u32_e32 v112, 0xa200, v110
	v_add_f32_e32 v103, 1.0, v103
	v_mul_f32_e32 v102, 0xbfb8aa3b, v102
	v_cmp_gt_f32_e32 vcc, s31, v103
	v_exp_f32_e32 v107, v102
	s_nop 0
	v_cndmask_b32_e64 v102, 0, 32, vcc
	v_ldexp_f32 v102, v103, v102
	v_log_f32_e32 v103, v102
	v_add_u32_e32 v102, v100, v148
	v_mul_f32_e32 v111, 0x3f317217, v103
	v_fma_f32 v111, v103, s1, -v111
	v_fmac_f32_e32 v111, 0x3377d1cf, v103
	v_fmac_f32_e32 v111, 0x3f317217, v103
	v_cmp_lt_f32_e64 s[42:43], |v103|, s33
	s_nop 1
	v_cndmask_b32_e64 v103, v103, v111, s[42:43]
	v_cndmask_b32_e32 v111, 0, v199, vcc
	v_sub_f32_e32 v103, v103, v111
	v_add_f32_e32 v103, v106, v103
	v_sub_f32_e32 v103, -0.5, v103
	v_mul_f32_e32 v103, 0x3fb8aa3b, v103
	v_exp_f32_e32 v106, v103
	v_mov_b32_e32 v103, v1
	v_lshl_add_u64 v[102:103], v[102:103], 2, s[48:49]
	global_store_dword v[102:103], v107, off
	v_mul_f32_e32 v102, 0xbfb8aa3b, v106
	v_add_f32_e32 v106, v28, v156
	v_mul_f32_e64 v103, |v106|, s0
	v_exp_f32_e32 v103, v103
	v_max_f32_e64 v106, -v106, 0
	v_exp_f32_e32 v107, v102
	v_add_u32_e32 v102, v100, v112
	v_add_f32_e32 v103, 1.0, v103
	v_cmp_gt_f32_e32 vcc, s31, v103
	s_nop 1
	v_cndmask_b32_e64 v111, 0, 32, vcc
	v_ldexp_f32 v103, v103, v111
	v_log_f32_e32 v111, v103
	v_mov_b32_e32 v103, v1
	v_lshl_add_u64 v[102:103], v[102:103], 2, s[48:49]
	global_store_dword v[102:103], v107, off
	v_mul_f32_e32 v157, 0x3f317217, v111
	v_fma_f32 v157, v111, s1, -v157
	v_fmac_f32_e32 v157, 0x3377d1cf, v111
	v_fmac_f32_e32 v157, 0x3f317217, v111
	v_cmp_lt_f32_e64 s[42:43], |v111|, s33
	s_nop 1
	v_cndmask_b32_e64 v111, v111, v157, s[42:43]
	v_cndmask_b32_e32 v157, 0, v199, vcc
	v_sub_f32_e32 v111, v111, v157
	v_add_f32_e32 v106, v106, v111
	v_sub_f32_e32 v106, -0.5, v106
	v_mul_f32_e32 v106, 0x3fb8aa3b, v106
	v_add_f32_e32 v157, v29, v156
	v_exp_f32_e32 v106, v106
	v_mul_f32_e64 v111, |v157|, s0
	v_exp_f32_e32 v111, v111
	v_max_f32_e64 v107, -v157, 0
	v_mul_f32_e32 v102, 0xbfb8aa3b, v106
	v_exp_f32_e32 v106, v102
	v_add_f32_e32 v102, 1.0, v111
	v_cmp_gt_f32_e32 vcc, s31, v102
	v_add_u32_e32 v111, 0xa400, v110
	s_nop 0
	v_cndmask_b32_e64 v103, 0, 32, vcc
	v_ldexp_f32 v102, v102, v103
	v_log_f32_e32 v103, v102
	v_add_u32_e32 v102, v100, v111
	v_mul_f32_e32 v157, 0x3f317217, v103
	v_fma_f32 v157, v103, s1, -v157
	v_fmac_f32_e32 v157, 0x3377d1cf, v103
	v_fmac_f32_e32 v157, 0x3f317217, v103
	v_cmp_lt_f32_e64 s[42:43], |v103|, s33
	s_nop 1
	v_cndmask_b32_e64 v103, v103, v157, s[42:43]
	v_cndmask_b32_e32 v157, 0, v199, vcc
	v_sub_f32_e32 v103, v103, v157
	v_add_f32_e32 v103, v107, v103
	v_sub_f32_e32 v103, -0.5, v103
	v_mul_f32_e32 v103, 0x3fb8aa3b, v103
	v_exp_f32_e32 v107, v103
	v_mov_b32_e32 v103, v1
	v_lshl_add_u64 v[102:103], v[102:103], 2, s[48:49]
	global_store_dword v[102:103], v106, off
	v_mul_f32_e32 v102, 0xbfb8aa3b, v107
	v_exp_f32_e32 v103, v102
	v_add_u32_e32 v102, 0xa600, v110
	v_add_u32_e32 v106, v100, v102
	v_mov_b32_e32 v107, v1
	v_lshl_add_u64 v[106:107], v[106:107], 2, s[48:49]
	global_store_dword v[106:107], v103, off
	v_add_f32_e32 v103, v30, v156
	v_max_f32_e64 v106, -v103, 0
	v_mul_f32_e64 v103, |v103|, s0
	v_exp_f32_e32 v103, v103
	v_mov_b32_e32 v159, v1
	v_add_f32_e32 v103, 1.0, v103
	v_cmp_gt_f32_e32 vcc, s31, v103
	s_nop 1
	v_cndmask_b32_e64 v107, 0, 32, vcc
	v_ldexp_f32 v103, v103, v107
	v_log_f32_e32 v103, v103
	s_nop 0
	v_mul_f32_e32 v107, 0x3f317217, v103
	v_fma_f32 v107, v103, s1, -v107
	v_fmac_f32_e32 v107, 0x3377d1cf, v103
	v_fmac_f32_e32 v107, 0x3f317217, v103
	v_cmp_lt_f32_e64 s[42:43], |v103|, s33
	s_nop 1
	v_cndmask_b32_e64 v103, v103, v107, s[42:43]
	v_cndmask_b32_e32 v107, 0, v199, vcc
	v_sub_f32_e32 v103, v103, v107
	v_add_f32_e32 v103, v106, v103
	v_sub_f32_e32 v103, -0.5, v103
	v_mul_f32_e32 v103, 0x3fb8aa3b, v103
	v_exp_f32_e32 v103, v103
	v_mov_b32_e32 v107, v1
	v_mul_f32_e32 v103, 0xbfb8aa3b, v103
	v_exp_f32_e32 v157, v103
	v_add_u32_e32 v103, 0xb000, v110
	v_add_u32_e32 v106, v100, v103
	v_lshl_add_u64 v[106:107], v[106:107], 2, s[48:49]
	global_store_dword v[106:107], v157, off
	v_add_f32_e32 v106, v31, v156
	v_max_f32_e64 v107, -v106, 0
	v_mul_f32_e64 v106, |v106|, s0
	v_exp_f32_e32 v106, v106
	s_nop 0
	v_add_f32_e32 v106, 1.0, v106
	v_cmp_gt_f32_e32 vcc, s31, v106
	s_nop 1
	v_cndmask_b32_e64 v157, 0, 32, vcc
	v_ldexp_f32 v106, v106, v157
	v_log_f32_e32 v106, v106
	s_nop 0
	v_mul_f32_e32 v157, 0x3f317217, v106
	v_fma_f32 v157, v106, s1, -v157
	v_fmac_f32_e32 v157, 0x3377d1cf, v106
	v_fmac_f32_e32 v157, 0x3f317217, v106
	v_cmp_lt_f32_e64 s[42:43], |v106|, s33
	s_nop 1
	v_cndmask_b32_e64 v106, v106, v157, s[42:43]
	v_cndmask_b32_e32 v157, 0, v199, vcc
	v_sub_f32_e32 v106, v106, v157
	v_add_f32_e32 v106, v107, v106
	v_sub_f32_e32 v106, -0.5, v106
	v_mul_f32_e32 v106, 0x3fb8aa3b, v106
	v_exp_f32_e32 v106, v106
	s_nop 0
	v_mul_f32_e32 v106, 0xbfb8aa3b, v106
	v_exp_f32_e32 v107, v106
	v_add_u32_e32 v106, 0xb200, v110
	v_add_u32_e32 v158, v100, v106
	v_lshl_add_u64 v[158:159], v[158:159], 2, s[48:49]
	global_store_dword v[158:159], v107, off
	v_add_f32_e32 v107, v32, v156
	v_max_f32_e64 v157, -v107, 0
	v_mul_f32_e64 v107, |v107|, s0
	v_exp_f32_e32 v107, v107
	v_mov_b32_e32 v159, v1
	v_add_f32_e32 v156, v33, v156
	v_add_f32_e32 v107, 1.0, v107
	v_cmp_gt_f32_e32 vcc, s31, v107
	s_nop 1
	v_cndmask_b32_e64 v158, 0, 32, vcc
	v_ldexp_f32 v107, v107, v158
	v_log_f32_e32 v107, v107
	s_nop 0
	v_mul_f32_e32 v158, 0x3f317217, v107
	v_fma_f32 v158, v107, s1, -v158
	v_fmac_f32_e32 v158, 0x3377d1cf, v107
	v_fmac_f32_e32 v158, 0x3f317217, v107
	v_cmp_lt_f32_e64 s[42:43], |v107|, s33
	s_nop 1
	v_cndmask_b32_e64 v107, v107, v158, s[42:43]
	v_cndmask_b32_e32 v158, 0, v199, vcc
	v_sub_f32_e32 v107, v107, v158
	v_add_f32_e32 v107, v157, v107
	v_sub_f32_e32 v107, -0.5, v107
	v_mul_f32_e32 v107, 0x3fb8aa3b, v107
	v_exp_f32_e32 v107, v107
	s_nop 0
	v_mul_f32_e32 v107, 0xbfb8aa3b, v107
	v_exp_f32_e32 v157, v107
	v_add_u32_e32 v107, 0xb400, v110
	v_add_u32_e32 v158, v100, v107
	v_lshl_add_u64 v[158:159], v[158:159], 2, s[48:49]
	global_store_dword v[158:159], v157, off
	v_max_f32_e64 v157, -v156, 0
	v_mul_f32_e64 v156, |v156|, s0
	v_exp_f32_e32 v156, v156
	v_add_u32_e32 v110, 0xb600, v110
	v_add_f32_e32 v156, 1.0, v156
	v_cmp_gt_f32_e32 vcc, s31, v156
	s_nop 1
	v_cndmask_b32_e64 v158, 0, 32, vcc
	v_ldexp_f32 v156, v156, v158
	v_log_f32_e32 v156, v156
	s_nop 0
	v_mul_f32_e32 v158, 0x3f317217, v156
	v_fma_f32 v158, v156, s1, -v158
	v_fmac_f32_e32 v158, 0x3377d1cf, v156
	v_fmac_f32_e32 v158, 0x3f317217, v156
	v_cmp_lt_f32_e64 s[42:43], |v156|, s33
	s_nop 1
	v_cndmask_b32_e64 v156, v156, v158, s[42:43]
	v_cndmask_b32_e32 v158, 0, v199, vcc
	v_sub_f32_e32 v156, v156, v158
	v_add_f32_e32 v156, v157, v156
	v_sub_f32_e32 v156, -0.5, v156
	v_mul_f32_e32 v156, 0x3fb8aa3b, v156
	v_exp_f32_e32 v156, v156
	v_mov_b32_e32 v157, v1
	v_mul_f32_e32 v156, 0xbfb8aa3b, v156
	v_exp_f32_e32 v158, v156
	v_add_u32_e32 v156, v100, v110
	v_lshl_add_u64 v[156:157], v[156:157], 2, s[48:49]
	global_store_dword v[156:157], v158, off
	v_mov_b32_e32 v104, v237
	v_add_f32_e32 v105, v2, v104
	v_max_f32_e64 v156, -v105, 0
	v_mul_f32_e64 v105, |v105|, s0
	v_exp_f32_e32 v105, v105
	v_add_u32_e32 v154, v101, v154
	v_add_f32_e32 v105, 1.0, v105
	v_cmp_gt_f32_e32 vcc, s31, v105
	s_nop 1
	v_cndmask_b32_e64 v157, 0, 32, vcc
	v_ldexp_f32 v105, v105, v157
	v_log_f32_e32 v105, v105
	s_nop 0
	v_mul_f32_e32 v157, 0x3f317217, v105
	v_fma_f32 v157, v105, s1, -v157
	v_fmac_f32_e32 v157, 0x3377d1cf, v105
	v_fmac_f32_e32 v157, 0x3f317217, v105
	v_cmp_lt_f32_e64 s[42:43], |v105|, s33
	s_nop 1
	v_cndmask_b32_e64 v105, v105, v157, s[42:43]
	v_cndmask_b32_e32 v157, 0, v199, vcc
	v_sub_f32_e32 v105, v105, v157
	v_add_f32_e32 v105, v156, v105
	v_sub_f32_e32 v105, -0.5, v105
	v_mul_f32_e32 v105, 0x3fb8aa3b, v105
	v_exp_f32_e32 v105, v105
	v_add_u32_e32 v156, v101, v155
	v_mov_b32_e32 v157, v1
	v_lshl_add_u64 v[156:157], v[156:157], 2, s[48:49]
	v_mul_f32_e32 v105, 0xbfb8aa3b, v105
	v_exp_f32_e32 v105, v105
	global_store_dword v[156:157], v105, off
	v_add_f32_e32 v105, v3, v104
	v_max_f32_e64 v155, -v105, 0
	v_mul_f32_e64 v105, |v105|, s0
	v_exp_f32_e32 v105, v105
	s_nop 0
	v_add_f32_e32 v105, 1.0, v105
	v_cmp_gt_f32_e32 vcc, s31, v105
	s_nop 1
	v_cndmask_b32_e64 v156, 0, 32, vcc
	v_ldexp_f32 v105, v105, v156
	v_log_f32_e32 v105, v105
	s_nop 0
	v_mul_f32_e32 v156, 0x3f317217, v105
	v_fma_f32 v156, v105, s1, -v156
	v_fmac_f32_e32 v156, 0x3377d1cf, v105
	v_fmac_f32_e32 v156, 0x3f317217, v105
	v_cmp_lt_f32_e64 s[42:43], |v105|, s33
	s_nop 1
	v_cndmask_b32_e64 v105, v105, v156, s[42:43]
	v_cndmask_b32_e32 v156, 0, v199, vcc
	v_sub_f32_e32 v105, v105, v156
	v_add_f32_e32 v105, v155, v105
	v_sub_f32_e32 v105, -0.5, v105
	v_mul_f32_e32 v105, 0x3fb8aa3b, v105
	v_exp_f32_e32 v105, v105
	v_mov_b32_e32 v155, v1
	v_lshl_add_u64 v[154:155], v[154:155], 2, s[48:49]
	v_mul_f32_e32 v105, 0xbfb8aa3b, v105
	v_exp_f32_e32 v105, v105
	global_store_dword v[154:155], v105, off
	v_add_f32_e32 v105, v4, v104
	v_max_f32_e64 v154, -v105, 0
	v_mul_f32_e64 v105, |v105|, s0
	v_exp_f32_e32 v105, v105
	s_nop 0
	v_add_f32_e32 v105, 1.0, v105
	v_cmp_gt_f32_e32 vcc, s31, v105
	s_nop 1
	v_cndmask_b32_e64 v155, 0, 32, vcc
	v_ldexp_f32 v105, v105, v155
	v_log_f32_e32 v105, v105
	s_nop 0
	v_mul_f32_e32 v155, 0x3f317217, v105
	v_fma_f32 v155, v105, s1, -v155
	v_fmac_f32_e32 v155, 0x3377d1cf, v105
	v_fmac_f32_e32 v155, 0x3f317217, v105
	v_cmp_lt_f32_e64 s[42:43], |v105|, s33
	s_nop 1
	v_cndmask_b32_e64 v105, v105, v155, s[42:43]
	v_cndmask_b32_e32 v155, 0, v199, vcc
	v_sub_f32_e32 v105, v105, v155
	v_add_f32_e32 v105, v154, v105
	v_sub_f32_e32 v105, -0.5, v105
	v_mul_f32_e32 v105, 0x3fb8aa3b, v105
	v_exp_f32_e32 v105, v105
	v_add_u32_e32 v154, v101, v153
	v_mov_b32_e32 v155, v1
	v_lshl_add_u64 v[154:155], v[154:155], 2, s[48:49]
	v_mul_f32_e32 v105, 0xbfb8aa3b, v105
	v_exp_f32_e32 v105, v105
	global_store_dword v[154:155], v105, off
	v_add_f32_e32 v105, v5, v104
	v_max_f32_e64 v153, -v105, 0
	v_mul_f32_e64 v105, |v105|, s0
	v_exp_f32_e32 v105, v105
	v_mov_b32_e32 v155, v1
	v_add_f32_e32 v105, 1.0, v105
	v_cmp_gt_f32_e32 vcc, s31, v105
	s_nop 1
	v_cndmask_b32_e64 v154, 0, 32, vcc
	v_ldexp_f32 v105, v105, v154
	v_log_f32_e32 v105, v105
	s_nop 0
	v_mul_f32_e32 v154, 0x3f317217, v105
	v_fma_f32 v154, v105, s1, -v154
	v_fmac_f32_e32 v154, 0x3377d1cf, v105
	v_fmac_f32_e32 v154, 0x3f317217, v105
	v_cmp_lt_f32_e64 s[42:43], |v105|, s33
	s_nop 1
	v_cndmask_b32_e64 v105, v105, v154, s[42:43]
	v_cndmask_b32_e32 v154, 0, v199, vcc
	v_sub_f32_e32 v105, v105, v154
	v_add_f32_e32 v105, v153, v105
	v_sub_f32_e32 v105, -0.5, v105
	v_mul_f32_e32 v105, 0x3fb8aa3b, v105
	v_exp_f32_e32 v105, v105
	v_add_u32_e32 v154, v101, v151
	v_lshl_add_u64 v[154:155], v[154:155], 2, s[48:49]
	v_mul_f32_e32 v105, 0xbfb8aa3b, v105
	v_exp_f32_e32 v105, v105
	global_store_dword v[154:155], v105, off
	v_add_f32_e32 v105, v6, v104
	v_max_f32_e64 v151, -v105, 0
	v_mul_f32_e64 v105, |v105|, s0
	v_exp_f32_e32 v105, v105
	v_add_u32_e32 v152, v101, v152
	v_add_u32_e32 v150, v101, v150
	v_add_f32_e32 v105, 1.0, v105
	v_cmp_gt_f32_e32 vcc, s31, v105
	s_nop 1
	v_cndmask_b32_e64 v153, 0, 32, vcc
	v_ldexp_f32 v105, v105, v153
	v_log_f32_e32 v105, v105
	s_nop 0
	v_mul_f32_e32 v153, 0x3f317217, v105
	v_fma_f32 v153, v105, s1, -v153
	v_fmac_f32_e32 v153, 0x3377d1cf, v105
	v_fmac_f32_e32 v153, 0x3f317217, v105
	v_cmp_lt_f32_e64 s[42:43], |v105|, s33
	s_nop 1
	v_cndmask_b32_e64 v105, v105, v153, s[42:43]
	v_cndmask_b32_e32 v153, 0, v199, vcc
	v_sub_f32_e32 v105, v105, v153
	v_add_f32_e32 v105, v151, v105
	v_sub_f32_e32 v105, -0.5, v105
	v_mul_f32_e32 v105, 0x3fb8aa3b, v105
	v_exp_f32_e32 v105, v105
	v_mov_b32_e32 v153, v1
	v_lshl_add_u64 v[152:153], v[152:153], 2, s[48:49]
	v_mul_f32_e32 v105, 0xbfb8aa3b, v105
	v_exp_f32_e32 v105, v105
	global_store_dword v[152:153], v105, off
	v_add_f32_e32 v105, v7, v104
	v_max_f32_e64 v151, -v105, 0
	v_mul_f32_e64 v105, |v105|, s0
	v_exp_f32_e32 v105, v105
	s_nop 0
	v_add_f32_e32 v105, 1.0, v105
	v_cmp_gt_f32_e32 vcc, s31, v105
	s_nop 1
	v_cndmask_b32_e64 v152, 0, 32, vcc
	v_ldexp_f32 v105, v105, v152
	v_log_f32_e32 v105, v105
	s_nop 0
	v_mul_f32_e32 v152, 0x3f317217, v105
	v_fma_f32 v152, v105, s1, -v152
	v_fmac_f32_e32 v152, 0x3377d1cf, v105
	v_fmac_f32_e32 v152, 0x3f317217, v105
	v_cmp_lt_f32_e64 s[42:43], |v105|, s33
	s_nop 1
	v_cndmask_b32_e64 v105, v105, v152, s[42:43]
	v_cndmask_b32_e32 v152, 0, v199, vcc
	v_sub_f32_e32 v105, v105, v152
	v_add_f32_e32 v105, v151, v105
	v_sub_f32_e32 v105, -0.5, v105
	v_mul_f32_e32 v105, 0x3fb8aa3b, v105
	v_exp_f32_e32 v105, v105
	v_mov_b32_e32 v151, v1
	v_lshl_add_u64 v[150:151], v[150:151], 2, s[48:49]
	v_mul_f32_e32 v105, 0xbfb8aa3b, v105
	v_exp_f32_e32 v105, v105
	global_store_dword v[150:151], v105, off
	v_add_f32_e32 v105, v8, v104
	v_max_f32_e64 v150, -v105, 0
	v_mul_f32_e64 v105, |v105|, s0
	v_exp_f32_e32 v105, v105
	s_nop 0
	v_add_f32_e32 v105, 1.0, v105
	v_cmp_gt_f32_e32 vcc, s31, v105
	s_nop 1
	v_cndmask_b32_e64 v151, 0, 32, vcc
	v_ldexp_f32 v105, v105, v151
	v_log_f32_e32 v105, v105
	s_nop 0
	v_mul_f32_e32 v151, 0x3f317217, v105
	v_fma_f32 v151, v105, s1, -v151
	v_fmac_f32_e32 v151, 0x3377d1cf, v105
	v_fmac_f32_e32 v151, 0x3f317217, v105
	v_cmp_lt_f32_e64 s[42:43], |v105|, s33
	s_nop 1
	v_cndmask_b32_e64 v105, v105, v151, s[42:43]
	v_cndmask_b32_e32 v151, 0, v199, vcc
	v_sub_f32_e32 v105, v105, v151
	v_add_f32_e32 v105, v150, v105
	v_sub_f32_e32 v105, -0.5, v105
	v_mul_f32_e32 v105, 0x3fb8aa3b, v105
	v_exp_f32_e32 v105, v105
	v_add_u32_e32 v150, v101, v149
	v_mov_b32_e32 v151, v1
	v_lshl_add_u64 v[150:151], v[150:151], 2, s[48:49]
	v_mul_f32_e32 v105, 0xbfb8aa3b, v105
	v_exp_f32_e32 v105, v105
	global_store_dword v[150:151], v105, off
	v_add_f32_e32 v105, v9, v104
	v_max_f32_e64 v149, -v105, 0
	v_mul_f32_e64 v105, |v105|, s0
	v_exp_f32_e32 v105, v105
	v_mov_b32_e32 v151, v1
	v_add_f32_e32 v105, 1.0, v105
	v_cmp_gt_f32_e32 vcc, s31, v105
	s_nop 1
	v_cndmask_b32_e64 v150, 0, 32, vcc
	v_ldexp_f32 v105, v105, v150
	v_log_f32_e32 v105, v105
	s_nop 0
	v_mul_f32_e32 v150, 0x3f317217, v105
	v_fma_f32 v150, v105, s1, -v150
	v_fmac_f32_e32 v150, 0x3377d1cf, v105
	v_fmac_f32_e32 v150, 0x3f317217, v105
	v_cmp_lt_f32_e64 s[42:43], |v105|, s33
	s_nop 1
	v_cndmask_b32_e64 v105, v105, v150, s[42:43]
	v_cndmask_b32_e32 v150, 0, v199, vcc
	v_sub_f32_e32 v105, v105, v150
	v_add_f32_e32 v105, v149, v105
	v_sub_f32_e32 v105, -0.5, v105
	v_mul_f32_e32 v105, 0x3fb8aa3b, v105
	v_exp_f32_e32 v105, v105
	v_add_u32_e32 v150, v101, v113
	v_lshl_add_u64 v[150:151], v[150:151], 2, s[48:49]
	v_mul_f32_e32 v105, 0xbfb8aa3b, v105
	v_exp_f32_e32 v105, v105
	global_store_dword v[150:151], v105, off
	v_add_f32_e32 v105, v10, v104
	v_max_f32_e64 v113, -v105, 0
	v_mul_f32_e64 v105, |v105|, s0
	v_exp_f32_e32 v105, v105
	v_add_u32_e32 v148, v101, v148
	v_add_u32_e32 v112, v101, v112
	v_add_f32_e32 v105, 1.0, v105
	v_cmp_gt_f32_e32 vcc, s31, v105
	s_nop 1
	v_cndmask_b32_e64 v149, 0, 32, vcc
	v_ldexp_f32 v105, v105, v149
	v_log_f32_e32 v105, v105
	s_nop 0
	v_mul_f32_e32 v149, 0x3f317217, v105
	v_fma_f32 v149, v105, s1, -v149
	v_fmac_f32_e32 v149, 0x3377d1cf, v105
	v_fmac_f32_e32 v149, 0x3f317217, v105
	v_cmp_lt_f32_e64 s[42:43], |v105|, s33
	s_nop 1
	v_cndmask_b32_e64 v105, v105, v149, s[42:43]
	v_cndmask_b32_e32 v149, 0, v199, vcc
	v_sub_f32_e32 v105, v105, v149
	v_add_f32_e32 v105, v113, v105
	v_sub_f32_e32 v105, -0.5, v105
	v_mul_f32_e32 v105, 0x3fb8aa3b, v105
	v_exp_f32_e32 v105, v105
	v_mov_b32_e32 v149, v1
	v_lshl_add_u64 v[148:149], v[148:149], 2, s[48:49]
	v_mul_f32_e32 v105, 0xbfb8aa3b, v105
	v_exp_f32_e32 v105, v105
	global_store_dword v[148:149], v105, off
	v_add_f32_e32 v105, v11, v104
	v_max_f32_e64 v113, -v105, 0
	v_mul_f32_e64 v105, |v105|, s0
	v_exp_f32_e32 v105, v105
	s_nop 0
	v_add_f32_e32 v105, 1.0, v105
	v_cmp_gt_f32_e32 vcc, s31, v105
	s_nop 1
	v_cndmask_b32_e64 v148, 0, 32, vcc
	v_ldexp_f32 v105, v105, v148
	v_log_f32_e32 v105, v105
	s_nop 0
	v_mul_f32_e32 v148, 0x3f317217, v105
	v_fma_f32 v148, v105, s1, -v148
	v_fmac_f32_e32 v148, 0x3377d1cf, v105
	v_fmac_f32_e32 v148, 0x3f317217, v105
	v_cmp_lt_f32_e64 s[42:43], |v105|, s33
	s_nop 1
	v_cndmask_b32_e64 v105, v105, v148, s[42:43]
	v_cndmask_b32_e32 v148, 0, v199, vcc
	v_sub_f32_e32 v105, v105, v148
	v_add_f32_e32 v105, v113, v105
	v_sub_f32_e32 v105, -0.5, v105
	v_mul_f32_e32 v105, 0x3fb8aa3b, v105
	v_exp_f32_e32 v105, v105
	v_mov_b32_e32 v113, v1
	v_lshl_add_u64 v[112:113], v[112:113], 2, s[48:49]
	v_mul_f32_e32 v105, 0xbfb8aa3b, v105
	v_exp_f32_e32 v105, v105
	global_store_dword v[112:113], v105, off
	v_add_f32_e32 v105, v12, v104
	v_max_f32_e64 v112, -v105, 0
	v_mul_f32_e64 v105, |v105|, s0
	v_exp_f32_e32 v105, v105
	s_nop 0
	v_add_f32_e32 v105, 1.0, v105
	v_cmp_gt_f32_e32 vcc, s31, v105
	s_nop 1
	v_cndmask_b32_e64 v113, 0, 32, vcc
	v_ldexp_f32 v105, v105, v113
	v_log_f32_e32 v105, v105
	s_nop 0
	v_mul_f32_e32 v113, 0x3f317217, v105
	v_fma_f32 v113, v105, s1, -v113
	v_fmac_f32_e32 v113, 0x3377d1cf, v105
	v_fmac_f32_e32 v113, 0x3f317217, v105
	v_cmp_lt_f32_e64 s[42:43], |v105|, s33
	s_nop 1
	v_cndmask_b32_e64 v105, v105, v113, s[42:43]
	v_cndmask_b32_e32 v113, 0, v199, vcc
	v_sub_f32_e32 v105, v105, v113
	v_add_f32_e32 v105, v112, v105
	v_sub_f32_e32 v105, -0.5, v105
	v_mul_f32_e32 v105, 0x3fb8aa3b, v105
	v_exp_f32_e32 v105, v105
	v_add_u32_e32 v112, v101, v111
	v_mov_b32_e32 v113, v1
	v_lshl_add_u64 v[112:113], v[112:113], 2, s[48:49]
	v_mul_f32_e32 v105, 0xbfb8aa3b, v105
	v_exp_f32_e32 v105, v105
	global_store_dword v[112:113], v105, off
	v_add_f32_e32 v105, v13, v104
	v_max_f32_e64 v111, -v105, 0
	v_mul_f32_e64 v105, |v105|, s0
	v_exp_f32_e32 v105, v105
	v_mov_b32_e32 v113, v1
	v_add_f32_e32 v105, 1.0, v105
	v_cmp_gt_f32_e32 vcc, s31, v105
	s_nop 1
	v_cndmask_b32_e64 v112, 0, 32, vcc
	v_ldexp_f32 v105, v105, v112
	v_log_f32_e32 v105, v105
	s_nop 0
	v_mul_f32_e32 v112, 0x3f317217, v105
	v_fma_f32 v112, v105, s1, -v112
	v_fmac_f32_e32 v112, 0x3377d1cf, v105
	v_fmac_f32_e32 v112, 0x3f317217, v105
	v_cmp_lt_f32_e64 s[42:43], |v105|, s33
	s_nop 1
	v_cndmask_b32_e64 v105, v105, v112, s[42:43]
	v_cndmask_b32_e32 v112, 0, v199, vcc
	v_sub_f32_e32 v105, v105, v112
	v_add_f32_e32 v105, v111, v105
	v_sub_f32_e32 v105, -0.5, v105
	v_mul_f32_e32 v105, 0x3fb8aa3b, v105
	v_exp_f32_e32 v105, v105
	v_add_u32_e32 v112, v101, v102
	v_lshl_add_u64 v[112:113], v[112:113], 2, s[48:49]
	v_mul_f32_e32 v105, 0xbfb8aa3b, v105
	v_exp_f32_e32 v105, v105
	global_store_dword v[112:113], v105, off
	v_add_f32_e32 v102, v14, v104
	v_max_f32_e64 v105, -v102, 0
	v_mul_f32_e64 v102, |v102|, s0
	v_exp_f32_e32 v102, v102
	s_nop 0
	v_add_f32_e32 v102, 1.0, v102
	v_cmp_gt_f32_e32 vcc, s31, v102
	s_nop 1
	v_cndmask_b32_e64 v111, 0, 32, vcc
	v_ldexp_f32 v102, v102, v111
	v_log_f32_e32 v102, v102
	s_nop 0
	v_mul_f32_e32 v111, 0x3f317217, v102
	v_fma_f32 v111, v102, s1, -v111
	v_fmac_f32_e32 v111, 0x3377d1cf, v102
	v_fmac_f32_e32 v111, 0x3f317217, v102
	v_cmp_lt_f32_e64 s[42:43], |v102|, s33
	s_nop 1
	v_cndmask_b32_e64 v102, v102, v111, s[42:43]
	v_cndmask_b32_e32 v111, 0, v199, vcc
	v_sub_f32_e32 v102, v102, v111
	v_add_f32_e32 v102, v105, v102
	v_sub_f32_e32 v102, -0.5, v102
	v_mul_f32_e32 v102, 0x3fb8aa3b, v102
	v_exp_f32_e32 v102, v102
	s_nop 0
	v_mul_f32_e32 v102, 0xbfb8aa3b, v102
	v_exp_f32_e32 v105, v102
	v_add_u32_e32 v102, v101, v103
	v_mov_b32_e32 v103, v1
	v_lshl_add_u64 v[102:103], v[102:103], 2, s[48:49]
	global_store_dword v[102:103], v105, off
	v_add_f32_e32 v102, v15, v104
	v_max_f32_e64 v103, -v102, 0
	v_mul_f32_e64 v102, |v102|, s0
	v_exp_f32_e32 v102, v102
	s_nop 0
	v_add_f32_e32 v102, 1.0, v102
	v_cmp_gt_f32_e32 vcc, s31, v102
	s_nop 1
	v_cndmask_b32_e64 v105, 0, 32, vcc
	v_ldexp_f32 v102, v102, v105
	v_log_f32_e32 v102, v102
	s_nop 0
	v_mul_f32_e32 v105, 0x3f317217, v102
	v_fma_f32 v105, v102, s1, -v105
	v_fmac_f32_e32 v105, 0x3377d1cf, v102
	v_fmac_f32_e32 v105, 0x3f317217, v102
	v_cmp_lt_f32_e64 s[42:43], |v102|, s33
	s_nop 1
	v_cndmask_b32_e64 v102, v102, v105, s[42:43]
	v_cndmask_b32_e32 v105, 0, v199, vcc
	v_sub_f32_e32 v102, v102, v105
	v_add_f32_e32 v102, v103, v102
	v_sub_f32_e32 v102, -0.5, v102
	v_mul_f32_e32 v102, 0x3fb8aa3b, v102
	v_exp_f32_e32 v102, v102
	v_mov_b32_e32 v103, v1
	v_mul_f32_e32 v102, 0xbfb8aa3b, v102
	v_exp_f32_e32 v105, v102
	v_add_u32_e32 v102, v101, v106
	v_lshl_add_u64 v[102:103], v[102:103], 2, s[48:49]
	global_store_dword v[102:103], v105, off
	v_add_f32_e32 v102, v16, v104
	v_max_f32_e64 v103, -v102, 0
	v_mul_f32_e64 v102, |v102|, s0
	v_exp_f32_e32 v102, v102
	s_nop 0
	v_add_f32_e32 v102, 1.0, v102
	v_cmp_gt_f32_e32 vcc, s31, v102
	s_nop 1
	v_cndmask_b32_e64 v105, 0, 32, vcc
	v_ldexp_f32 v102, v102, v105
	v_log_f32_e32 v102, v102
	s_nop 0
	v_mul_f32_e32 v105, 0x3f317217, v102
	v_fma_f32 v105, v102, s1, -v105
	v_fmac_f32_e32 v105, 0x3377d1cf, v102
	v_fmac_f32_e32 v105, 0x3f317217, v102
	v_cmp_lt_f32_e64 s[42:43], |v102|, s33
	s_nop 1
	v_cndmask_b32_e64 v102, v102, v105, s[42:43]
	v_cndmask_b32_e32 v105, 0, v199, vcc
	v_sub_f32_e32 v102, v102, v105
	v_add_f32_e32 v102, v103, v102
	v_sub_f32_e32 v102, -0.5, v102
	v_mul_f32_e32 v102, 0x3fb8aa3b, v102
	v_exp_f32_e32 v102, v102
	v_mov_b32_e32 v103, v1
	v_mul_f32_e32 v102, 0xbfb8aa3b, v102
	v_exp_f32_e32 v105, v102
	v_add_u32_e32 v102, v101, v107
	v_lshl_add_u64 v[102:103], v[102:103], 2, s[48:49]
	global_store_dword v[102:103], v105, off
	v_add_f32_e32 v102, v17, v104
	v_max_f32_e64 v103, -v102, 0
	v_mul_f32_e64 v102, |v102|, s0
	v_exp_f32_e32 v102, v102
	s_nop 0
	v_add_f32_e32 v102, 1.0, v102
	v_cmp_gt_f32_e32 vcc, s31, v102
	s_nop 1
	v_cndmask_b32_e64 v104, 0, 32, vcc
	v_ldexp_f32 v102, v102, v104
	v_log_f32_e32 v102, v102
	s_nop 0
	v_mul_f32_e32 v104, 0x3f317217, v102
	v_fma_f32 v104, v102, s1, -v104
	v_fmac_f32_e32 v104, 0x3377d1cf, v102
	v_fmac_f32_e32 v104, 0x3f317217, v102
	v_cmp_lt_f32_e64 s[42:43], |v102|, s33
	s_nop 1
	v_cndmask_b32_e64 v102, v102, v104, s[42:43]
	v_cndmask_b32_e32 v104, 0, v199, vcc
	v_sub_f32_e32 v102, v102, v104
	v_add_f32_e32 v102, v103, v102
	v_sub_f32_e32 v102, -0.5, v102
	v_mul_f32_e32 v102, 0x3fb8aa3b, v102
	v_exp_f32_e32 v102, v102
	v_mov_b32_e32 v103, v1
	v_mul_f32_e32 v102, 0xbfb8aa3b, v102
	v_exp_f32_e32 v104, v102
	v_add_u32_e32 v102, v101, v110
	v_lshl_add_u64 v[102:103], v[102:103], 2, s[48:49]
	global_store_dword v[102:103], v104, off
